# gemm256 k-loops rewritten as fully interleaved schedule (B-fragment-major MFMA groups, just-in-time LDS reads, barrier after 3rd block); merge kloopS writes interleaved
# speedup vs baseline: 1.0423x; 1.0194x over previous
.LBB0_85:
	v_add3_u32 v238, v232, v233, v236
	v_add3_u32 v239, v234, v233, v237
	v_add3_u32 v236, v232, v235, v236
	v_add3_u32 v237, v234, v235, v237
	v_add_u32_e32 v236, 0x10000, v236
	v_add_u32_e32 v237, 0x10000, v237
	v_add_u32_e32 v254, 0x8000, v229
	v_add_u32_e32 v255, 0x8000, v230
	ds_read_b128 v[164:167], v238
	ds_read_b128 v[168:171], v238 offset:256
	ds_read_b128 v[172:175], v238 offset:512
	ds_read_b128 v[192:195], v238 offset:768
	ds_read_b128 v[176:179], v236
	ds_read_b128 v[180:183], v236 offset:256
	ds_read_b128 v[184:187], v236 offset:512
	ds_read_b128 v[188:191], v236 offset:768
	ds_read_b128 v[196:199], v238 offset:1024
	ds_read_b128 v[200:203], v238 offset:1280
	ds_read_b128 v[204:207], v238 offset:1536
	ds_read_b128 v[208:211], v238 offset:1792
	s_nop 0
	v_xor_b32_e32 v238, 0x8000, v238
	v_xor_b32_e32 v236, 0x8000, v236
.Lg1_loop:
	s_add_i32 s47, s46, 1
	s_cmp_ge_i32 s47, s3
	s_cbranch_scc1 .Lg1_cold
	s_add_i32 s46, s46, 2
	s_cmp_ge_i32 s46, s3
	s_cbranch_scc1 .Lg1_warm
	v_add_u32_e32 v246, v227, v228
	v_add_u32_e32 v247, v227, v231
	v_lshlrev_b32_e32 v246, 1, v246
	v_lshlrev_b32_e32 v247, 1, v247
	v_add_u32_e32 v248, 0x80000, v246
	v_add_u32_e32 v249, 0x100000, v246
	v_add_u32_e32 v250, 0x180000, v246
	v_add_u32_e32 v251, 0x80000, v247
	v_add_u32_e32 v252, 0x100000, v247
	v_add_u32_e32 v253, 0x180000, v247
	s_waitcnt lgkmcnt(7)
	v_mfma_f32_16x16x32_f16 v[148:151], v[176:179], v[164:167], v[148:151]
	v_mfma_f32_16x16x32_f16 v[112:115], v[176:179], v[168:171], v[112:115]
	v_mfma_f32_16x16x32_f16 v[96:99], v[176:179], v[172:175], v[96:99]
	v_mfma_f32_16x16x32_f16 v[80:83], v[176:179], v[192:195], v[80:83]
	s_waitcnt vmcnt(7)
	ds_write_b128 v254, v[124:127]
	global_load_dwordx4 v[124:127], v246, s[30:31] offset:256
	s_waitcnt lgkmcnt(7)
	v_mfma_f32_16x16x32_f16 v[128:131], v[180:183], v[164:167], v[128:131]
	v_mfma_f32_16x16x32_f16 v[108:111], v[180:183], v[168:171], v[108:111]
	v_mfma_f32_16x16x32_f16 v[92:95], v[180:183], v[172:175], v[92:95]
	v_mfma_f32_16x16x32_f16 v[76:79], v[180:183], v[192:195], v[76:79]
	s_waitcnt vmcnt(7)
	ds_write_b128 v254, v[132:135] offset:1024
	global_load_dwordx4 v[132:135], v248, s[30:31] offset:256
	s_waitcnt lgkmcnt(7)
	v_mfma_f32_16x16x32_f16 v[120:123], v[184:187], v[164:167], v[120:123]
	v_mfma_f32_16x16x32_f16 v[104:107], v[184:187], v[168:171], v[104:107]
	v_mfma_f32_16x16x32_f16 v[88:91], v[184:187], v[172:175], v[88:91]
	v_mfma_f32_16x16x32_f16 v[72:75], v[184:187], v[192:195], v[72:75]
	s_waitcnt vmcnt(7)
	ds_write_b128 v254, v[136:139] offset:2048
	global_load_dwordx4 v[136:139], v249, s[30:31] offset:256
	s_waitcnt lgkmcnt(7)
	v_mfma_f32_16x16x32_f16 v[116:119], v[188:191], v[164:167], v[116:119]
	v_mfma_f32_16x16x32_f16 v[100:103], v[188:191], v[168:171], v[100:103]
	v_mfma_f32_16x16x32_f16 v[84:87], v[188:191], v[172:175], v[84:87]
	v_mfma_f32_16x16x32_f16 v[68:71], v[188:191], v[192:195], v[68:71]
	s_waitcnt vmcnt(7)
	ds_write_b128 v254, v[140:143] offset:3072
	global_load_dwordx4 v[140:143], v250, s[30:31] offset:256
	ds_read_b128 v[164:167], v239
	ds_read_b128 v[168:171], v239 offset:256
	ds_read_b128 v[172:175], v239 offset:512
	ds_read_b128 v[192:195], v239 offset:768
	s_waitcnt lgkmcnt(11)
	v_mfma_f32_16x16x32_f16 v[64:67], v[176:179], v[196:199], v[64:67]
	s_waitcnt lgkmcnt(10)
	v_mfma_f32_16x16x32_f16 v[48:51], v[176:179], v[200:203], v[48:51]
	s_waitcnt lgkmcnt(9)
	v_mfma_f32_16x16x32_f16 v[30:33], v[176:179], v[204:207], v[30:33]
	s_waitcnt lgkmcnt(8)
	v_mfma_f32_16x16x32_f16 v[14:17], v[176:179], v[208:211], v[14:17]
	ds_read_b128 v[176:179], v237
	s_waitcnt vmcnt(7)
	ds_write_b128 v255, v[144:147]
	global_load_dwordx4 v[144:147], v247, s[38:39] offset:256
	v_mfma_f32_16x16x32_f16 v[60:63], v[180:183], v[196:199], v[60:63]
	v_mfma_f32_16x16x32_f16 v[44:47], v[180:183], v[200:203], v[44:47]
	v_mfma_f32_16x16x32_f16 v[26:29], v[180:183], v[204:207], v[26:29]
	v_mfma_f32_16x16x32_f16 v[10:13], v[180:183], v[208:211], v[10:13]
	ds_read_b128 v[180:183], v237 offset:256
	s_waitcnt vmcnt(7)
	ds_write_b128 v255, v[152:155] offset:1024
	global_load_dwordx4 v[152:155], v251, s[38:39] offset:256
	v_mfma_f32_16x16x32_f16 v[56:59], v[184:187], v[196:199], v[56:59]
	v_mfma_f32_16x16x32_f16 v[40:43], v[184:187], v[200:203], v[40:43]
	v_mfma_f32_16x16x32_f16 v[22:25], v[184:187], v[204:207], v[22:25]
	v_mfma_f32_16x16x32_f16 v[6:9], v[184:187], v[208:211], v[6:9]
	ds_read_b128 v[184:187], v237 offset:512
	s_waitcnt vmcnt(7)
	ds_write_b128 v255, v[156:159] offset:2048
	global_load_dwordx4 v[156:159], v252, s[38:39] offset:256
	v_mfma_f32_16x16x32_f16 v[52:55], v[188:191], v[196:199], v[52:55]
	v_mfma_f32_16x16x32_f16 v[36:39], v[188:191], v[200:203], v[36:39]
	v_mfma_f32_16x16x32_f16 v[18:21], v[188:191], v[204:207], v[18:21]
	v_mfma_f32_16x16x32_f16 v[2:5], v[188:191], v[208:211], v[2:5]
	ds_read_b128 v[188:191], v237 offset:768
	s_waitcnt vmcnt(7)
	ds_write_b128 v255, v[160:163] offset:3072
	global_load_dwordx4 v[160:163], v253, s[38:39] offset:256
	ds_read_b128 v[196:199], v239 offset:1024
	ds_read_b128 v[200:203], v239 offset:1280
	ds_read_b128 v[204:207], v239 offset:1536
	ds_read_b128 v[208:211], v239 offset:1792
	s_waitcnt lgkmcnt(11)
	v_mfma_f32_16x16x32_f16 v[148:151], v[176:179], v[164:167], v[148:151]
	v_mfma_f32_16x16x32_f16 v[112:115], v[176:179], v[168:171], v[112:115]
	v_mfma_f32_16x16x32_f16 v[96:99], v[176:179], v[172:175], v[96:99]
	v_mfma_f32_16x16x32_f16 v[80:83], v[176:179], v[192:195], v[80:83]
	s_waitcnt lgkmcnt(9)
	v_mfma_f32_16x16x32_f16 v[128:131], v[180:183], v[164:167], v[128:131]
	v_mfma_f32_16x16x32_f16 v[108:111], v[180:183], v[168:171], v[108:111]
	v_mfma_f32_16x16x32_f16 v[92:95], v[180:183], v[172:175], v[92:95]
	v_mfma_f32_16x16x32_f16 v[76:79], v[180:183], v[192:195], v[76:79]
	s_waitcnt lgkmcnt(7)
	v_mfma_f32_16x16x32_f16 v[120:123], v[184:187], v[164:167], v[120:123]
	v_mfma_f32_16x16x32_f16 v[104:107], v[184:187], v[168:171], v[104:107]
	v_mfma_f32_16x16x32_f16 v[88:91], v[184:187], v[172:175], v[88:91]
	v_mfma_f32_16x16x32_f16 v[72:75], v[184:187], v[192:195], v[72:75]
	s_waitcnt lgkmcnt(5)
	v_mfma_f32_16x16x32_f16 v[116:119], v[188:191], v[164:167], v[116:119]
	v_mfma_f32_16x16x32_f16 v[100:103], v[188:191], v[168:171], v[100:103]
	v_mfma_f32_16x16x32_f16 v[84:87], v[188:191], v[172:175], v[84:87]
	v_mfma_f32_16x16x32_f16 v[68:71], v[188:191], v[192:195], v[68:71]
	s_waitcnt lgkmcnt(0)
	s_barrier
	ds_read_b128 v[164:167], v238
	ds_read_b128 v[168:171], v238 offset:256
	ds_read_b128 v[172:175], v238 offset:512
	ds_read_b128 v[192:195], v238 offset:768
	v_mfma_f32_16x16x32_f16 v[64:67], v[176:179], v[196:199], v[64:67]
	v_mfma_f32_16x16x32_f16 v[48:51], v[176:179], v[200:203], v[48:51]
	v_mfma_f32_16x16x32_f16 v[30:33], v[176:179], v[204:207], v[30:33]
	v_mfma_f32_16x16x32_f16 v[14:17], v[176:179], v[208:211], v[14:17]
	ds_read_b128 v[176:179], v236
	v_mfma_f32_16x16x32_f16 v[60:63], v[180:183], v[196:199], v[60:63]
	v_mfma_f32_16x16x32_f16 v[44:47], v[180:183], v[200:203], v[44:47]
	v_mfma_f32_16x16x32_f16 v[26:29], v[180:183], v[204:207], v[26:29]
	v_mfma_f32_16x16x32_f16 v[10:13], v[180:183], v[208:211], v[10:13]
	ds_read_b128 v[180:183], v236 offset:256
	v_mfma_f32_16x16x32_f16 v[56:59], v[184:187], v[196:199], v[56:59]
	v_mfma_f32_16x16x32_f16 v[40:43], v[184:187], v[200:203], v[40:43]
	v_mfma_f32_16x16x32_f16 v[22:25], v[184:187], v[204:207], v[22:25]
	v_mfma_f32_16x16x32_f16 v[6:9], v[184:187], v[208:211], v[6:9]
	ds_read_b128 v[184:187], v236 offset:512
	v_mfma_f32_16x16x32_f16 v[52:55], v[188:191], v[196:199], v[52:55]
	v_mfma_f32_16x16x32_f16 v[36:39], v[188:191], v[200:203], v[36:39]
	v_mfma_f32_16x16x32_f16 v[18:21], v[188:191], v[204:207], v[18:21]
	v_mfma_f32_16x16x32_f16 v[2:5], v[188:191], v[208:211], v[2:5]
	ds_read_b128 v[188:191], v236 offset:768
	ds_read_b128 v[196:199], v238 offset:1024
	ds_read_b128 v[200:203], v238 offset:1280
	ds_read_b128 v[204:207], v238 offset:1536
	ds_read_b128 v[208:211], v238 offset:1792
	v_xor_b32_e32 v239, 0x8000, v239
	v_xor_b32_e32 v237, 0x8000, v237
	v_xor_b32_e32 v254, 0x8000, v254
	v_xor_b32_e32 v255, 0x8000, v255
	v_xor_b32_e32 v236, 0x8000, v236
	v_xor_b32_e32 v238, 0x8000, v238
	s_addk_i32 s45, 0x800
	v_add_u32_e32 v231, 64, v231
	v_add_u32_e32 v228, 64, v228
	s_mov_b32 s46, s47
	s_branch .Lg1_loop
.Lg1_warm:
	s_waitcnt lgkmcnt(7)
	v_mfma_f32_16x16x32_f16 v[148:151], v[176:179], v[164:167], v[148:151]
	v_mfma_f32_16x16x32_f16 v[112:115], v[176:179], v[168:171], v[112:115]
	v_mfma_f32_16x16x32_f16 v[96:99], v[176:179], v[172:175], v[96:99]
	v_mfma_f32_16x16x32_f16 v[80:83], v[176:179], v[192:195], v[80:83]
	s_waitcnt vmcnt(7)
	ds_write_b128 v254, v[124:127]
	s_waitcnt lgkmcnt(7)
	v_mfma_f32_16x16x32_f16 v[128:131], v[180:183], v[164:167], v[128:131]
	v_mfma_f32_16x16x32_f16 v[108:111], v[180:183], v[168:171], v[108:111]
	v_mfma_f32_16x16x32_f16 v[92:95], v[180:183], v[172:175], v[92:95]
	v_mfma_f32_16x16x32_f16 v[76:79], v[180:183], v[192:195], v[76:79]
	s_waitcnt vmcnt(6)
	ds_write_b128 v254, v[132:135] offset:1024
	s_waitcnt lgkmcnt(7)
	v_mfma_f32_16x16x32_f16 v[120:123], v[184:187], v[164:167], v[120:123]
	v_mfma_f32_16x16x32_f16 v[104:107], v[184:187], v[168:171], v[104:107]
	v_mfma_f32_16x16x32_f16 v[88:91], v[184:187], v[172:175], v[88:91]
	v_mfma_f32_16x16x32_f16 v[72:75], v[184:187], v[192:195], v[72:75]
	s_waitcnt vmcnt(5)
	ds_write_b128 v254, v[136:139] offset:2048
	s_waitcnt lgkmcnt(7)
	v_mfma_f32_16x16x32_f16 v[116:119], v[188:191], v[164:167], v[116:119]
	v_mfma_f32_16x16x32_f16 v[100:103], v[188:191], v[168:171], v[100:103]
	v_mfma_f32_16x16x32_f16 v[84:87], v[188:191], v[172:175], v[84:87]
	v_mfma_f32_16x16x32_f16 v[68:71], v[188:191], v[192:195], v[68:71]
	s_waitcnt vmcnt(4)
	ds_write_b128 v254, v[140:143] offset:3072
	ds_read_b128 v[164:167], v239
	ds_read_b128 v[168:171], v239 offset:256
	ds_read_b128 v[172:175], v239 offset:512
	ds_read_b128 v[192:195], v239 offset:768
	s_waitcnt lgkmcnt(11)
	v_mfma_f32_16x16x32_f16 v[64:67], v[176:179], v[196:199], v[64:67]
	s_waitcnt lgkmcnt(10)
	v_mfma_f32_16x16x32_f16 v[48:51], v[176:179], v[200:203], v[48:51]
	s_waitcnt lgkmcnt(9)
	v_mfma_f32_16x16x32_f16 v[30:33], v[176:179], v[204:207], v[30:33]
	s_waitcnt lgkmcnt(8)
	v_mfma_f32_16x16x32_f16 v[14:17], v[176:179], v[208:211], v[14:17]
	ds_read_b128 v[176:179], v237
	s_waitcnt vmcnt(3)
	ds_write_b128 v255, v[144:147]
	v_mfma_f32_16x16x32_f16 v[60:63], v[180:183], v[196:199], v[60:63]
	v_mfma_f32_16x16x32_f16 v[44:47], v[180:183], v[200:203], v[44:47]
	v_mfma_f32_16x16x32_f16 v[26:29], v[180:183], v[204:207], v[26:29]
	v_mfma_f32_16x16x32_f16 v[10:13], v[180:183], v[208:211], v[10:13]
	ds_read_b128 v[180:183], v237 offset:256
	s_waitcnt vmcnt(2)
	ds_write_b128 v255, v[152:155] offset:1024
	v_mfma_f32_16x16x32_f16 v[56:59], v[184:187], v[196:199], v[56:59]
	v_mfma_f32_16x16x32_f16 v[40:43], v[184:187], v[200:203], v[40:43]
	v_mfma_f32_16x16x32_f16 v[22:25], v[184:187], v[204:207], v[22:25]
	v_mfma_f32_16x16x32_f16 v[6:9], v[184:187], v[208:211], v[6:9]
	ds_read_b128 v[184:187], v237 offset:512
	s_waitcnt vmcnt(1)
	ds_write_b128 v255, v[156:159] offset:2048
	v_mfma_f32_16x16x32_f16 v[52:55], v[188:191], v[196:199], v[52:55]
	v_mfma_f32_16x16x32_f16 v[36:39], v[188:191], v[200:203], v[36:39]
	v_mfma_f32_16x16x32_f16 v[18:21], v[188:191], v[204:207], v[18:21]
	v_mfma_f32_16x16x32_f16 v[2:5], v[188:191], v[208:211], v[2:5]
	ds_read_b128 v[188:191], v237 offset:768
	s_waitcnt vmcnt(0)
	ds_write_b128 v255, v[160:163] offset:3072
	ds_read_b128 v[196:199], v239 offset:1024
	ds_read_b128 v[200:203], v239 offset:1280
	ds_read_b128 v[204:207], v239 offset:1536
	ds_read_b128 v[208:211], v239 offset:1792
	s_waitcnt lgkmcnt(11)
	v_mfma_f32_16x16x32_f16 v[148:151], v[176:179], v[164:167], v[148:151]
	v_mfma_f32_16x16x32_f16 v[112:115], v[176:179], v[168:171], v[112:115]
	v_mfma_f32_16x16x32_f16 v[96:99], v[176:179], v[172:175], v[96:99]
	v_mfma_f32_16x16x32_f16 v[80:83], v[176:179], v[192:195], v[80:83]
	s_waitcnt lgkmcnt(9)
	v_mfma_f32_16x16x32_f16 v[128:131], v[180:183], v[164:167], v[128:131]
	v_mfma_f32_16x16x32_f16 v[108:111], v[180:183], v[168:171], v[108:111]
	v_mfma_f32_16x16x32_f16 v[92:95], v[180:183], v[172:175], v[92:95]
	v_mfma_f32_16x16x32_f16 v[76:79], v[180:183], v[192:195], v[76:79]
	s_waitcnt lgkmcnt(7)
	v_mfma_f32_16x16x32_f16 v[120:123], v[184:187], v[164:167], v[120:123]
	v_mfma_f32_16x16x32_f16 v[104:107], v[184:187], v[168:171], v[104:107]
	v_mfma_f32_16x16x32_f16 v[88:91], v[184:187], v[172:175], v[88:91]
	v_mfma_f32_16x16x32_f16 v[72:75], v[184:187], v[192:195], v[72:75]
	s_waitcnt lgkmcnt(5)
	v_mfma_f32_16x16x32_f16 v[116:119], v[188:191], v[164:167], v[116:119]
	v_mfma_f32_16x16x32_f16 v[100:103], v[188:191], v[168:171], v[100:103]
	v_mfma_f32_16x16x32_f16 v[84:87], v[188:191], v[172:175], v[84:87]
	v_mfma_f32_16x16x32_f16 v[68:71], v[188:191], v[192:195], v[68:71]
	s_waitcnt lgkmcnt(0)
	s_barrier
	ds_read_b128 v[164:167], v238
	ds_read_b128 v[168:171], v238 offset:256
	ds_read_b128 v[172:175], v238 offset:512
	ds_read_b128 v[192:195], v238 offset:768
	v_mfma_f32_16x16x32_f16 v[64:67], v[176:179], v[196:199], v[64:67]
	v_mfma_f32_16x16x32_f16 v[48:51], v[176:179], v[200:203], v[48:51]
	v_mfma_f32_16x16x32_f16 v[30:33], v[176:179], v[204:207], v[30:33]
	v_mfma_f32_16x16x32_f16 v[14:17], v[176:179], v[208:211], v[14:17]
	ds_read_b128 v[176:179], v236
	v_mfma_f32_16x16x32_f16 v[60:63], v[180:183], v[196:199], v[60:63]
	v_mfma_f32_16x16x32_f16 v[44:47], v[180:183], v[200:203], v[44:47]
	v_mfma_f32_16x16x32_f16 v[26:29], v[180:183], v[204:207], v[26:29]
	v_mfma_f32_16x16x32_f16 v[10:13], v[180:183], v[208:211], v[10:13]
	ds_read_b128 v[180:183], v236 offset:256
	v_mfma_f32_16x16x32_f16 v[56:59], v[184:187], v[196:199], v[56:59]
	v_mfma_f32_16x16x32_f16 v[40:43], v[184:187], v[200:203], v[40:43]
	v_mfma_f32_16x16x32_f16 v[22:25], v[184:187], v[204:207], v[22:25]
	v_mfma_f32_16x16x32_f16 v[6:9], v[184:187], v[208:211], v[6:9]
	ds_read_b128 v[184:187], v236 offset:512
	v_mfma_f32_16x16x32_f16 v[52:55], v[188:191], v[196:199], v[52:55]
	v_mfma_f32_16x16x32_f16 v[36:39], v[188:191], v[200:203], v[36:39]
	v_mfma_f32_16x16x32_f16 v[18:21], v[188:191], v[204:207], v[18:21]
	v_mfma_f32_16x16x32_f16 v[2:5], v[188:191], v[208:211], v[2:5]
	ds_read_b128 v[188:191], v236 offset:768
	ds_read_b128 v[196:199], v238 offset:1024
	ds_read_b128 v[200:203], v238 offset:1280
	ds_read_b128 v[204:207], v238 offset:1536
	ds_read_b128 v[208:211], v238 offset:1792
	v_xor_b32_e32 v239, 0x8000, v239
	v_xor_b32_e32 v237, 0x8000, v237
	v_xor_b32_e32 v254, 0x8000, v254
	v_xor_b32_e32 v255, 0x8000, v255
	v_xor_b32_e32 v236, 0x8000, v236
	v_xor_b32_e32 v238, 0x8000, v238
	s_addk_i32 s45, 0x800
	v_add_u32_e32 v231, 64, v231
	v_add_u32_e32 v228, 64, v228
	s_mov_b32 s46, s47
	s_branch .Lg1_loop
.Lg1_cold:
	s_waitcnt lgkmcnt(7)
	v_mfma_f32_16x16x32_f16 v[148:151], v[176:179], v[164:167], v[148:151]
	v_mfma_f32_16x16x32_f16 v[112:115], v[176:179], v[168:171], v[112:115]
	v_mfma_f32_16x16x32_f16 v[96:99], v[176:179], v[172:175], v[96:99]
	v_mfma_f32_16x16x32_f16 v[80:83], v[176:179], v[192:195], v[80:83]
	s_waitcnt lgkmcnt(6)
	v_mfma_f32_16x16x32_f16 v[128:131], v[180:183], v[164:167], v[128:131]
	v_mfma_f32_16x16x32_f16 v[108:111], v[180:183], v[168:171], v[108:111]
	v_mfma_f32_16x16x32_f16 v[92:95], v[180:183], v[172:175], v[92:95]
	v_mfma_f32_16x16x32_f16 v[76:79], v[180:183], v[192:195], v[76:79]
	s_waitcnt lgkmcnt(5)
	v_mfma_f32_16x16x32_f16 v[120:123], v[184:187], v[164:167], v[120:123]
	v_mfma_f32_16x16x32_f16 v[104:107], v[184:187], v[168:171], v[104:107]
	v_mfma_f32_16x16x32_f16 v[88:91], v[184:187], v[172:175], v[88:91]
	v_mfma_f32_16x16x32_f16 v[72:75], v[184:187], v[192:195], v[72:75]
	s_waitcnt lgkmcnt(4)
	v_mfma_f32_16x16x32_f16 v[116:119], v[188:191], v[164:167], v[116:119]
	v_mfma_f32_16x16x32_f16 v[100:103], v[188:191], v[168:171], v[100:103]
	v_mfma_f32_16x16x32_f16 v[84:87], v[188:191], v[172:175], v[84:87]
	v_mfma_f32_16x16x32_f16 v[68:71], v[188:191], v[192:195], v[68:71]
	ds_read_b128 v[164:167], v239
	ds_read_b128 v[168:171], v239 offset:256
	ds_read_b128 v[172:175], v239 offset:512
	ds_read_b128 v[192:195], v239 offset:768
	s_waitcnt lgkmcnt(7)
	v_mfma_f32_16x16x32_f16 v[64:67], v[176:179], v[196:199], v[64:67]
	s_waitcnt lgkmcnt(6)
	v_mfma_f32_16x16x32_f16 v[48:51], v[176:179], v[200:203], v[48:51]
	s_waitcnt lgkmcnt(5)
	v_mfma_f32_16x16x32_f16 v[30:33], v[176:179], v[204:207], v[30:33]
	s_waitcnt lgkmcnt(4)
	v_mfma_f32_16x16x32_f16 v[14:17], v[176:179], v[208:211], v[14:17]
	ds_read_b128 v[176:179], v237
	v_mfma_f32_16x16x32_f16 v[60:63], v[180:183], v[196:199], v[60:63]
	v_mfma_f32_16x16x32_f16 v[44:47], v[180:183], v[200:203], v[44:47]
	v_mfma_f32_16x16x32_f16 v[26:29], v[180:183], v[204:207], v[26:29]
	v_mfma_f32_16x16x32_f16 v[10:13], v[180:183], v[208:211], v[10:13]
	ds_read_b128 v[180:183], v237 offset:256
	v_mfma_f32_16x16x32_f16 v[56:59], v[184:187], v[196:199], v[56:59]
	v_mfma_f32_16x16x32_f16 v[40:43], v[184:187], v[200:203], v[40:43]
	v_mfma_f32_16x16x32_f16 v[22:25], v[184:187], v[204:207], v[22:25]
	v_mfma_f32_16x16x32_f16 v[6:9], v[184:187], v[208:211], v[6:9]
	ds_read_b128 v[184:187], v237 offset:512
	v_mfma_f32_16x16x32_f16 v[52:55], v[188:191], v[196:199], v[52:55]
	v_mfma_f32_16x16x32_f16 v[36:39], v[188:191], v[200:203], v[36:39]
	v_mfma_f32_16x16x32_f16 v[18:21], v[188:191], v[204:207], v[18:21]
	v_mfma_f32_16x16x32_f16 v[2:5], v[188:191], v[208:211], v[2:5]
	ds_read_b128 v[188:191], v237 offset:768
	ds_read_b128 v[196:199], v239 offset:1024
	ds_read_b128 v[200:203], v239 offset:1280
	ds_read_b128 v[204:207], v239 offset:1536
	ds_read_b128 v[208:211], v239 offset:1792
	s_waitcnt lgkmcnt(7)
	v_mfma_f32_16x16x32_f16 v[148:151], v[176:179], v[164:167], v[148:151]
	v_mfma_f32_16x16x32_f16 v[112:115], v[176:179], v[168:171], v[112:115]
	v_mfma_f32_16x16x32_f16 v[96:99], v[176:179], v[172:175], v[96:99]
	v_mfma_f32_16x16x32_f16 v[80:83], v[176:179], v[192:195], v[80:83]
	s_waitcnt lgkmcnt(6)
	v_mfma_f32_16x16x32_f16 v[128:131], v[180:183], v[164:167], v[128:131]
	v_mfma_f32_16x16x32_f16 v[108:111], v[180:183], v[168:171], v[108:111]
	v_mfma_f32_16x16x32_f16 v[92:95], v[180:183], v[172:175], v[92:95]
	v_mfma_f32_16x16x32_f16 v[76:79], v[180:183], v[192:195], v[76:79]
	s_waitcnt lgkmcnt(5)
	v_mfma_f32_16x16x32_f16 v[120:123], v[184:187], v[164:167], v[120:123]
	v_mfma_f32_16x16x32_f16 v[104:107], v[184:187], v[168:171], v[104:107]
	v_mfma_f32_16x16x32_f16 v[88:91], v[184:187], v[172:175], v[88:91]
	v_mfma_f32_16x16x32_f16 v[72:75], v[184:187], v[192:195], v[72:75]
	s_waitcnt lgkmcnt(4)
	v_mfma_f32_16x16x32_f16 v[116:119], v[188:191], v[164:167], v[116:119]
	v_mfma_f32_16x16x32_f16 v[100:103], v[188:191], v[168:171], v[100:103]
	v_mfma_f32_16x16x32_f16 v[84:87], v[188:191], v[172:175], v[84:87]
	v_mfma_f32_16x16x32_f16 v[68:71], v[188:191], v[192:195], v[68:71]
	s_waitcnt lgkmcnt(0)
	s_barrier
	v_mfma_f32_16x16x32_f16 v[64:67], v[176:179], v[196:199], v[64:67]
	v_mfma_f32_16x16x32_f16 v[48:51], v[176:179], v[200:203], v[48:51]
	v_mfma_f32_16x16x32_f16 v[30:33], v[176:179], v[204:207], v[30:33]
	v_mfma_f32_16x16x32_f16 v[14:17], v[176:179], v[208:211], v[14:17]
	v_mfma_f32_16x16x32_f16 v[60:63], v[180:183], v[196:199], v[60:63]
	v_mfma_f32_16x16x32_f16 v[44:47], v[180:183], v[200:203], v[44:47]
	v_mfma_f32_16x16x32_f16 v[26:29], v[180:183], v[204:207], v[26:29]
	v_mfma_f32_16x16x32_f16 v[10:13], v[180:183], v[208:211], v[10:13]
	v_mfma_f32_16x16x32_f16 v[56:59], v[184:187], v[196:199], v[56:59]
	v_mfma_f32_16x16x32_f16 v[40:43], v[184:187], v[200:203], v[40:43]
	v_mfma_f32_16x16x32_f16 v[22:25], v[184:187], v[204:207], v[22:25]
	v_mfma_f32_16x16x32_f16 v[6:9], v[184:187], v[208:211], v[6:9]
	v_mfma_f32_16x16x32_f16 v[52:55], v[188:191], v[196:199], v[52:55]
	v_mfma_f32_16x16x32_f16 v[36:39], v[188:191], v[200:203], v[36:39]
	v_mfma_f32_16x16x32_f16 v[18:21], v[188:191], v[204:207], v[18:21]
	v_mfma_f32_16x16x32_f16 v[2:5], v[188:191], v[208:211], v[2:5]
	s_branch .LBB0_91

.Lg2_loop:
	s_add_i32 s43, s42, 1
	s_cmp_ge_i32 s43, s3
	s_cbranch_scc1 .Lg2_cold
	s_add_i32 s42, s42, 2
	s_cmp_ge_i32 s42, s3
	s_cbranch_scc1 .Lg2_warm
	v_add_u32_e32 v246, v227, v228
	v_add_u32_e32 v247, v227, v231
	v_lshlrev_b32_e32 v246, 1, v246
	v_lshlrev_b32_e32 v247, 1, v247
	v_add_u32_e32 v248, 0x20000, v246
	v_add_u32_e32 v249, 0x40000, v246
	v_add_u32_e32 v250, 0x60000, v246
	v_add_u32_e32 v251, 0x20000, v247
	v_add_u32_e32 v252, 0x40000, v247
	v_add_u32_e32 v253, 0x60000, v247
	s_waitcnt lgkmcnt(7)
	v_mfma_f32_16x16x32_f16 v[156:159], v[176:179], v[164:167], v[156:159]
	v_mfma_f32_16x16x32_f16 v[112:115], v[176:179], v[168:171], v[112:115]
	v_mfma_f32_16x16x32_f16 v[96:99], v[176:179], v[172:175], v[96:99]
	v_mfma_f32_16x16x32_f16 v[80:83], v[176:179], v[192:195], v[80:83]
	s_waitcnt vmcnt(7)
	ds_write_b128 v254, v[116:119]
	global_load_dwordx4 v[116:119], v246, s[30:31] offset:256
	s_waitcnt lgkmcnt(7)
	v_mfma_f32_16x16x32_f16 v[148:151], v[180:183], v[164:167], v[148:151]
	v_mfma_f32_16x16x32_f16 v[108:111], v[180:183], v[168:171], v[108:111]
	v_mfma_f32_16x16x32_f16 v[92:95], v[180:183], v[172:175], v[92:95]
	v_mfma_f32_16x16x32_f16 v[76:79], v[180:183], v[192:195], v[76:79]
	s_waitcnt vmcnt(7)
	ds_write_b128 v254, v[120:123] offset:1024
	global_load_dwordx4 v[120:123], v248, s[30:31] offset:256
	s_waitcnt lgkmcnt(7)
	v_mfma_f32_16x16x32_f16 v[132:135], v[184:187], v[164:167], v[132:135]
	v_mfma_f32_16x16x32_f16 v[104:107], v[184:187], v[168:171], v[104:107]
	v_mfma_f32_16x16x32_f16 v[88:91], v[184:187], v[172:175], v[88:91]
	v_mfma_f32_16x16x32_f16 v[72:75], v[184:187], v[192:195], v[72:75]
	s_waitcnt vmcnt(7)
	ds_write_b128 v254, v[128:131] offset:2048
	global_load_dwordx4 v[128:131], v249, s[30:31] offset:256
	s_waitcnt lgkmcnt(7)
	v_mfma_f32_16x16x32_f16 v[124:127], v[188:191], v[164:167], v[124:127]
	v_mfma_f32_16x16x32_f16 v[100:103], v[188:191], v[168:171], v[100:103]
	v_mfma_f32_16x16x32_f16 v[84:87], v[188:191], v[172:175], v[84:87]
	v_mfma_f32_16x16x32_f16 v[68:71], v[188:191], v[192:195], v[68:71]
	s_waitcnt vmcnt(7)
	ds_write_b128 v254, v[136:139] offset:3072
	global_load_dwordx4 v[136:139], v250, s[30:31] offset:256
	ds_read_b128 v[164:167], v239
	ds_read_b128 v[168:171], v239 offset:256
	ds_read_b128 v[172:175], v239 offset:512
	ds_read_b128 v[192:195], v239 offset:768
	s_waitcnt lgkmcnt(11)
	v_mfma_f32_16x16x32_f16 v[64:67], v[176:179], v[196:199], v[64:67]
	s_waitcnt lgkmcnt(10)
	v_mfma_f32_16x16x32_f16 v[48:51], v[176:179], v[200:203], v[48:51]
	s_waitcnt lgkmcnt(9)
	v_mfma_f32_16x16x32_f16 v[30:33], v[176:179], v[204:207], v[30:33]
	s_waitcnt lgkmcnt(8)
	v_mfma_f32_16x16x32_f16 v[14:17], v[176:179], v[208:211], v[14:17]
	ds_read_b128 v[176:179], v237
	s_waitcnt vmcnt(7)
	ds_write_b128 v255, v[140:143]
	global_load_dwordx4 v[140:143], v247, s[38:39] offset:256
	v_mfma_f32_16x16x32_f16 v[60:63], v[180:183], v[196:199], v[60:63]
	v_mfma_f32_16x16x32_f16 v[44:47], v[180:183], v[200:203], v[44:47]
	v_mfma_f32_16x16x32_f16 v[26:29], v[180:183], v[204:207], v[26:29]
	v_mfma_f32_16x16x32_f16 v[10:13], v[180:183], v[208:211], v[10:13]
	ds_read_b128 v[180:183], v237 offset:256
	s_waitcnt vmcnt(7)
	ds_write_b128 v255, v[144:147] offset:1024
	global_load_dwordx4 v[144:147], v251, s[38:39] offset:256
	v_mfma_f32_16x16x32_f16 v[56:59], v[184:187], v[196:199], v[56:59]
	v_mfma_f32_16x16x32_f16 v[40:43], v[184:187], v[200:203], v[40:43]
	v_mfma_f32_16x16x32_f16 v[22:25], v[184:187], v[204:207], v[22:25]
	v_mfma_f32_16x16x32_f16 v[6:9], v[184:187], v[208:211], v[6:9]
	ds_read_b128 v[184:187], v237 offset:512
	s_waitcnt vmcnt(7)
	ds_write_b128 v255, v[152:155] offset:2048
	global_load_dwordx4 v[152:155], v252, s[38:39] offset:256
	v_mfma_f32_16x16x32_f16 v[52:55], v[188:191], v[196:199], v[52:55]
	v_mfma_f32_16x16x32_f16 v[36:39], v[188:191], v[200:203], v[36:39]
	v_mfma_f32_16x16x32_f16 v[18:21], v[188:191], v[204:207], v[18:21]
	v_mfma_f32_16x16x32_f16 v[2:5], v[188:191], v[208:211], v[2:5]
	ds_read_b128 v[188:191], v237 offset:768
	s_waitcnt vmcnt(7)
	ds_write_b128 v255, v[160:163] offset:3072
	global_load_dwordx4 v[160:163], v253, s[38:39] offset:256
	ds_read_b128 v[196:199], v239 offset:1024
	ds_read_b128 v[200:203], v239 offset:1280
	ds_read_b128 v[204:207], v239 offset:1536
	ds_read_b128 v[208:211], v239 offset:1792
	s_waitcnt lgkmcnt(11)
	v_mfma_f32_16x16x32_f16 v[156:159], v[176:179], v[164:167], v[156:159]
	v_mfma_f32_16x16x32_f16 v[112:115], v[176:179], v[168:171], v[112:115]
	v_mfma_f32_16x16x32_f16 v[96:99], v[176:179], v[172:175], v[96:99]
	v_mfma_f32_16x16x32_f16 v[80:83], v[176:179], v[192:195], v[80:83]
	s_waitcnt lgkmcnt(9)
	v_mfma_f32_16x16x32_f16 v[148:151], v[180:183], v[164:167], v[148:151]
	v_mfma_f32_16x16x32_f16 v[108:111], v[180:183], v[168:171], v[108:111]
	v_mfma_f32_16x16x32_f16 v[92:95], v[180:183], v[172:175], v[92:95]
	v_mfma_f32_16x16x32_f16 v[76:79], v[180:183], v[192:195], v[76:79]
	s_waitcnt lgkmcnt(7)
	v_mfma_f32_16x16x32_f16 v[132:135], v[184:187], v[164:167], v[132:135]
	v_mfma_f32_16x16x32_f16 v[104:107], v[184:187], v[168:171], v[104:107]
	v_mfma_f32_16x16x32_f16 v[88:91], v[184:187], v[172:175], v[88:91]
	v_mfma_f32_16x16x32_f16 v[72:75], v[184:187], v[192:195], v[72:75]
	s_waitcnt lgkmcnt(5)
	v_mfma_f32_16x16x32_f16 v[124:127], v[188:191], v[164:167], v[124:127]
	v_mfma_f32_16x16x32_f16 v[100:103], v[188:191], v[168:171], v[100:103]
	v_mfma_f32_16x16x32_f16 v[84:87], v[188:191], v[172:175], v[84:87]
	v_mfma_f32_16x16x32_f16 v[68:71], v[188:191], v[192:195], v[68:71]
	s_waitcnt lgkmcnt(0)
	s_barrier
	ds_read_b128 v[164:167], v238
	ds_read_b128 v[168:171], v238 offset:256
	ds_read_b128 v[172:175], v238 offset:512
	ds_read_b128 v[192:195], v238 offset:768
	v_mfma_f32_16x16x32_f16 v[64:67], v[176:179], v[196:199], v[64:67]
	v_mfma_f32_16x16x32_f16 v[48:51], v[176:179], v[200:203], v[48:51]
	v_mfma_f32_16x16x32_f16 v[30:33], v[176:179], v[204:207], v[30:33]
	v_mfma_f32_16x16x32_f16 v[14:17], v[176:179], v[208:211], v[14:17]
	ds_read_b128 v[176:179], v236
	v_mfma_f32_16x16x32_f16 v[60:63], v[180:183], v[196:199], v[60:63]
	v_mfma_f32_16x16x32_f16 v[44:47], v[180:183], v[200:203], v[44:47]
	v_mfma_f32_16x16x32_f16 v[26:29], v[180:183], v[204:207], v[26:29]
	v_mfma_f32_16x16x32_f16 v[10:13], v[180:183], v[208:211], v[10:13]
	ds_read_b128 v[180:183], v236 offset:256
	v_mfma_f32_16x16x32_f16 v[56:59], v[184:187], v[196:199], v[56:59]
	v_mfma_f32_16x16x32_f16 v[40:43], v[184:187], v[200:203], v[40:43]
	v_mfma_f32_16x16x32_f16 v[22:25], v[184:187], v[204:207], v[22:25]
	v_mfma_f32_16x16x32_f16 v[6:9], v[184:187], v[208:211], v[6:9]
	ds_read_b128 v[184:187], v236 offset:512
	v_mfma_f32_16x16x32_f16 v[52:55], v[188:191], v[196:199], v[52:55]
	v_mfma_f32_16x16x32_f16 v[36:39], v[188:191], v[200:203], v[36:39]
	v_mfma_f32_16x16x32_f16 v[18:21], v[188:191], v[204:207], v[18:21]
	v_mfma_f32_16x16x32_f16 v[2:5], v[188:191], v[208:211], v[2:5]
	ds_read_b128 v[188:191], v236 offset:768
	ds_read_b128 v[196:199], v238 offset:1024
	ds_read_b128 v[200:203], v238 offset:1280
	ds_read_b128 v[204:207], v238 offset:1536
	ds_read_b128 v[208:211], v238 offset:1792
	v_xor_b32_e32 v239, 0x8000, v239
	v_xor_b32_e32 v237, 0x8000, v237
	v_xor_b32_e32 v254, 0x8000, v254
	v_xor_b32_e32 v255, 0x8000, v255
	v_xor_b32_e32 v236, 0x8000, v236
	v_xor_b32_e32 v238, 0x8000, v238
	s_addk_i32 s23, 0x800
	v_add_u32_e32 v231, 64, v231
	v_add_u32_e32 v228, 64, v228
	s_mov_b32 s42, s43
	s_branch .Lg2_loop
.Lg2_warm:
	s_waitcnt lgkmcnt(7)
	v_mfma_f32_16x16x32_f16 v[156:159], v[176:179], v[164:167], v[156:159]
	v_mfma_f32_16x16x32_f16 v[112:115], v[176:179], v[168:171], v[112:115]
	v_mfma_f32_16x16x32_f16 v[96:99], v[176:179], v[172:175], v[96:99]
	v_mfma_f32_16x16x32_f16 v[80:83], v[176:179], v[192:195], v[80:83]
	s_waitcnt vmcnt(7)
	ds_write_b128 v254, v[116:119]
	s_waitcnt lgkmcnt(7)
	v_mfma_f32_16x16x32_f16 v[148:151], v[180:183], v[164:167], v[148:151]
	v_mfma_f32_16x16x32_f16 v[108:111], v[180:183], v[168:171], v[108:111]
	v_mfma_f32_16x16x32_f16 v[92:95], v[180:183], v[172:175], v[92:95]
	v_mfma_f32_16x16x32_f16 v[76:79], v[180:183], v[192:195], v[76:79]
	s_waitcnt vmcnt(6)
	ds_write_b128 v254, v[120:123] offset:1024
	s_waitcnt lgkmcnt(7)
	v_mfma_f32_16x16x32_f16 v[132:135], v[184:187], v[164:167], v[132:135]
	v_mfma_f32_16x16x32_f16 v[104:107], v[184:187], v[168:171], v[104:107]
	v_mfma_f32_16x16x32_f16 v[88:91], v[184:187], v[172:175], v[88:91]
	v_mfma_f32_16x16x32_f16 v[72:75], v[184:187], v[192:195], v[72:75]
	s_waitcnt vmcnt(5)
	ds_write_b128 v254, v[128:131] offset:2048
	s_waitcnt lgkmcnt(7)
	v_mfma_f32_16x16x32_f16 v[124:127], v[188:191], v[164:167], v[124:127]
	v_mfma_f32_16x16x32_f16 v[100:103], v[188:191], v[168:171], v[100:103]
	v_mfma_f32_16x16x32_f16 v[84:87], v[188:191], v[172:175], v[84:87]
	v_mfma_f32_16x16x32_f16 v[68:71], v[188:191], v[192:195], v[68:71]
	s_waitcnt vmcnt(4)
	ds_write_b128 v254, v[136:139] offset:3072
	ds_read_b128 v[164:167], v239
	ds_read_b128 v[168:171], v239 offset:256
	ds_read_b128 v[172:175], v239 offset:512
	ds_read_b128 v[192:195], v239 offset:768
	s_waitcnt lgkmcnt(11)
	v_mfma_f32_16x16x32_f16 v[64:67], v[176:179], v[196:199], v[64:67]
	s_waitcnt lgkmcnt(10)
	v_mfma_f32_16x16x32_f16 v[48:51], v[176:179], v[200:203], v[48:51]
	s_waitcnt lgkmcnt(9)
	v_mfma_f32_16x16x32_f16 v[30:33], v[176:179], v[204:207], v[30:33]
	s_waitcnt lgkmcnt(8)
	v_mfma_f32_16x16x32_f16 v[14:17], v[176:179], v[208:211], v[14:17]
	ds_read_b128 v[176:179], v237
	s_waitcnt vmcnt(3)
	ds_write_b128 v255, v[140:143]
	v_mfma_f32_16x16x32_f16 v[60:63], v[180:183], v[196:199], v[60:63]
	v_mfma_f32_16x16x32_f16 v[44:47], v[180:183], v[200:203], v[44:47]
	v_mfma_f32_16x16x32_f16 v[26:29], v[180:183], v[204:207], v[26:29]
	v_mfma_f32_16x16x32_f16 v[10:13], v[180:183], v[208:211], v[10:13]
	ds_read_b128 v[180:183], v237 offset:256
	s_waitcnt vmcnt(2)
	ds_write_b128 v255, v[144:147] offset:1024
	v_mfma_f32_16x16x32_f16 v[56:59], v[184:187], v[196:199], v[56:59]
	v_mfma_f32_16x16x32_f16 v[40:43], v[184:187], v[200:203], v[40:43]
	v_mfma_f32_16x16x32_f16 v[22:25], v[184:187], v[204:207], v[22:25]
	v_mfma_f32_16x16x32_f16 v[6:9], v[184:187], v[208:211], v[6:9]
	ds_read_b128 v[184:187], v237 offset:512
	s_waitcnt vmcnt(1)
	ds_write_b128 v255, v[152:155] offset:2048
	v_mfma_f32_16x16x32_f16 v[52:55], v[188:191], v[196:199], v[52:55]
	v_mfma_f32_16x16x32_f16 v[36:39], v[188:191], v[200:203], v[36:39]
	v_mfma_f32_16x16x32_f16 v[18:21], v[188:191], v[204:207], v[18:21]
	v_mfma_f32_16x16x32_f16 v[2:5], v[188:191], v[208:211], v[2:5]
	ds_read_b128 v[188:191], v237 offset:768
	s_waitcnt vmcnt(0)
	ds_write_b128 v255, v[160:163] offset:3072
	ds_read_b128 v[196:199], v239 offset:1024
	ds_read_b128 v[200:203], v239 offset:1280
	ds_read_b128 v[204:207], v239 offset:1536
	ds_read_b128 v[208:211], v239 offset:1792
	s_waitcnt lgkmcnt(11)
	v_mfma_f32_16x16x32_f16 v[156:159], v[176:179], v[164:167], v[156:159]
	v_mfma_f32_16x16x32_f16 v[112:115], v[176:179], v[168:171], v[112:115]
	v_mfma_f32_16x16x32_f16 v[96:99], v[176:179], v[172:175], v[96:99]
	v_mfma_f32_16x16x32_f16 v[80:83], v[176:179], v[192:195], v[80:83]
	s_waitcnt lgkmcnt(9)
	v_mfma_f32_16x16x32_f16 v[148:151], v[180:183], v[164:167], v[148:151]
	v_mfma_f32_16x16x32_f16 v[108:111], v[180:183], v[168:171], v[108:111]
	v_mfma_f32_16x16x32_f16 v[92:95], v[180:183], v[172:175], v[92:95]
	v_mfma_f32_16x16x32_f16 v[76:79], v[180:183], v[192:195], v[76:79]
	s_waitcnt lgkmcnt(7)
	v_mfma_f32_16x16x32_f16 v[132:135], v[184:187], v[164:167], v[132:135]
	v_mfma_f32_16x16x32_f16 v[104:107], v[184:187], v[168:171], v[104:107]
	v_mfma_f32_16x16x32_f16 v[88:91], v[184:187], v[172:175], v[88:91]
	v_mfma_f32_16x16x32_f16 v[72:75], v[184:187], v[192:195], v[72:75]
	s_waitcnt lgkmcnt(5)
	v_mfma_f32_16x16x32_f16 v[124:127], v[188:191], v[164:167], v[124:127]
	v_mfma_f32_16x16x32_f16 v[100:103], v[188:191], v[168:171], v[100:103]
	v_mfma_f32_16x16x32_f16 v[84:87], v[188:191], v[172:175], v[84:87]
	v_mfma_f32_16x16x32_f16 v[68:71], v[188:191], v[192:195], v[68:71]
	s_waitcnt lgkmcnt(0)
	s_barrier
	ds_read_b128 v[164:167], v238
	ds_read_b128 v[168:171], v238 offset:256
	ds_read_b128 v[172:175], v238 offset:512
	ds_read_b128 v[192:195], v238 offset:768
	v_mfma_f32_16x16x32_f16 v[64:67], v[176:179], v[196:199], v[64:67]
	v_mfma_f32_16x16x32_f16 v[48:51], v[176:179], v[200:203], v[48:51]
	v_mfma_f32_16x16x32_f16 v[30:33], v[176:179], v[204:207], v[30:33]
	v_mfma_f32_16x16x32_f16 v[14:17], v[176:179], v[208:211], v[14:17]
	ds_read_b128 v[176:179], v236
	v_mfma_f32_16x16x32_f16 v[60:63], v[180:183], v[196:199], v[60:63]
	v_mfma_f32_16x16x32_f16 v[44:47], v[180:183], v[200:203], v[44:47]
	v_mfma_f32_16x16x32_f16 v[26:29], v[180:183], v[204:207], v[26:29]
	v_mfma_f32_16x16x32_f16 v[10:13], v[180:183], v[208:211], v[10:13]
	ds_read_b128 v[180:183], v236 offset:256
	v_mfma_f32_16x16x32_f16 v[56:59], v[184:187], v[196:199], v[56:59]
	v_mfma_f32_16x16x32_f16 v[40:43], v[184:187], v[200:203], v[40:43]
	v_mfma_f32_16x16x32_f16 v[22:25], v[184:187], v[204:207], v[22:25]
	v_mfma_f32_16x16x32_f16 v[6:9], v[184:187], v[208:211], v[6:9]
	ds_read_b128 v[184:187], v236 offset:512
	v_mfma_f32_16x16x32_f16 v[52:55], v[188:191], v[196:199], v[52:55]
	v_mfma_f32_16x16x32_f16 v[36:39], v[188:191], v[200:203], v[36:39]
	v_mfma_f32_16x16x32_f16 v[18:21], v[188:191], v[204:207], v[18:21]
	v_mfma_f32_16x16x32_f16 v[2:5], v[188:191], v[208:211], v[2:5]
	ds_read_b128 v[188:191], v236 offset:768
	ds_read_b128 v[196:199], v238 offset:1024
	ds_read_b128 v[200:203], v238 offset:1280
	ds_read_b128 v[204:207], v238 offset:1536
	ds_read_b128 v[208:211], v238 offset:1792
	v_xor_b32_e32 v239, 0x8000, v239
	v_xor_b32_e32 v237, 0x8000, v237
	v_xor_b32_e32 v254, 0x8000, v254
	v_xor_b32_e32 v255, 0x8000, v255
	v_xor_b32_e32 v236, 0x8000, v236
	v_xor_b32_e32 v238, 0x8000, v238
	s_addk_i32 s23, 0x800
	v_add_u32_e32 v231, 64, v231
	v_add_u32_e32 v228, 64, v228
	s_mov_b32 s42, s43
	s_branch .Lg2_loop
.Lg2_cold:
	s_waitcnt lgkmcnt(7)
	v_mfma_f32_16x16x32_f16 v[156:159], v[176:179], v[164:167], v[156:159]
	v_mfma_f32_16x16x32_f16 v[112:115], v[176:179], v[168:171], v[112:115]
	v_mfma_f32_16x16x32_f16 v[96:99], v[176:179], v[172:175], v[96:99]
	v_mfma_f32_16x16x32_f16 v[80:83], v[176:179], v[192:195], v[80:83]
	s_waitcnt lgkmcnt(6)
	v_mfma_f32_16x16x32_f16 v[148:151], v[180:183], v[164:167], v[148:151]
	v_mfma_f32_16x16x32_f16 v[108:111], v[180:183], v[168:171], v[108:111]
	v_mfma_f32_16x16x32_f16 v[92:95], v[180:183], v[172:175], v[92:95]
	v_mfma_f32_16x16x32_f16 v[76:79], v[180:183], v[192:195], v[76:79]
	s_waitcnt lgkmcnt(5)
	v_mfma_f32_16x16x32_f16 v[132:135], v[184:187], v[164:167], v[132:135]
	v_mfma_f32_16x16x32_f16 v[104:107], v[184:187], v[168:171], v[104:107]
	v_mfma_f32_16x16x32_f16 v[88:91], v[184:187], v[172:175], v[88:91]
	v_mfma_f32_16x16x32_f16 v[72:75], v[184:187], v[192:195], v[72:75]
	s_waitcnt lgkmcnt(4)
	v_mfma_f32_16x16x32_f16 v[124:127], v[188:191], v[164:167], v[124:127]
	v_mfma_f32_16x16x32_f16 v[100:103], v[188:191], v[168:171], v[100:103]
	v_mfma_f32_16x16x32_f16 v[84:87], v[188:191], v[172:175], v[84:87]
	v_mfma_f32_16x16x32_f16 v[68:71], v[188:191], v[192:195], v[68:71]
	ds_read_b128 v[164:167], v239
	ds_read_b128 v[168:171], v239 offset:256
	ds_read_b128 v[172:175], v239 offset:512
	ds_read_b128 v[192:195], v239 offset:768
	s_waitcnt lgkmcnt(7)
	v_mfma_f32_16x16x32_f16 v[64:67], v[176:179], v[196:199], v[64:67]
	s_waitcnt lgkmcnt(6)
	v_mfma_f32_16x16x32_f16 v[48:51], v[176:179], v[200:203], v[48:51]
	s_waitcnt lgkmcnt(5)
	v_mfma_f32_16x16x32_f16 v[30:33], v[176:179], v[204:207], v[30:33]
	s_waitcnt lgkmcnt(4)
	v_mfma_f32_16x16x32_f16 v[14:17], v[176:179], v[208:211], v[14:17]
	ds_read_b128 v[176:179], v237
	v_mfma_f32_16x16x32_f16 v[60:63], v[180:183], v[196:199], v[60:63]
	v_mfma_f32_16x16x32_f16 v[44:47], v[180:183], v[200:203], v[44:47]
	v_mfma_f32_16x16x32_f16 v[26:29], v[180:183], v[204:207], v[26:29]
	v_mfma_f32_16x16x32_f16 v[10:13], v[180:183], v[208:211], v[10:13]
	ds_read_b128 v[180:183], v237 offset:256
	v_mfma_f32_16x16x32_f16 v[56:59], v[184:187], v[196:199], v[56:59]
	v_mfma_f32_16x16x32_f16 v[40:43], v[184:187], v[200:203], v[40:43]
	v_mfma_f32_16x16x32_f16 v[22:25], v[184:187], v[204:207], v[22:25]
	v_mfma_f32_16x16x32_f16 v[6:9], v[184:187], v[208:211], v[6:9]
	ds_read_b128 v[184:187], v237 offset:512
	v_mfma_f32_16x16x32_f16 v[52:55], v[188:191], v[196:199], v[52:55]
	v_mfma_f32_16x16x32_f16 v[36:39], v[188:191], v[200:203], v[36:39]
	v_mfma_f32_16x16x32_f16 v[18:21], v[188:191], v[204:207], v[18:21]
	v_mfma_f32_16x16x32_f16 v[2:5], v[188:191], v[208:211], v[2:5]
	ds_read_b128 v[188:191], v237 offset:768
	ds_read_b128 v[196:199], v239 offset:1024
	ds_read_b128 v[200:203], v239 offset:1280
	ds_read_b128 v[204:207], v239 offset:1536
	ds_read_b128 v[208:211], v239 offset:1792
	s_waitcnt lgkmcnt(7)
	v_mfma_f32_16x16x32_f16 v[156:159], v[176:179], v[164:167], v[156:159]
	v_mfma_f32_16x16x32_f16 v[112:115], v[176:179], v[168:171], v[112:115]
	v_mfma_f32_16x16x32_f16 v[96:99], v[176:179], v[172:175], v[96:99]
	v_mfma_f32_16x16x32_f16 v[80:83], v[176:179], v[192:195], v[80:83]
	s_waitcnt lgkmcnt(6)
	v_mfma_f32_16x16x32_f16 v[148:151], v[180:183], v[164:167], v[148:151]
	v_mfma_f32_16x16x32_f16 v[108:111], v[180:183], v[168:171], v[108:111]
	v_mfma_f32_16x16x32_f16 v[92:95], v[180:183], v[172:175], v[92:95]
	v_mfma_f32_16x16x32_f16 v[76:79], v[180:183], v[192:195], v[76:79]
	s_waitcnt lgkmcnt(5)
	v_mfma_f32_16x16x32_f16 v[132:135], v[184:187], v[164:167], v[132:135]
	v_mfma_f32_16x16x32_f16 v[104:107], v[184:187], v[168:171], v[104:107]
	v_mfma_f32_16x16x32_f16 v[88:91], v[184:187], v[172:175], v[88:91]
	v_mfma_f32_16x16x32_f16 v[72:75], v[184:187], v[192:195], v[72:75]
	s_waitcnt lgkmcnt(4)
	v_mfma_f32_16x16x32_f16 v[124:127], v[188:191], v[164:167], v[124:127]
	v_mfma_f32_16x16x32_f16 v[100:103], v[188:191], v[168:171], v[100:103]
	v_mfma_f32_16x16x32_f16 v[84:87], v[188:191], v[172:175], v[84:87]
	v_mfma_f32_16x16x32_f16 v[68:71], v[188:191], v[192:195], v[68:71]
	s_waitcnt lgkmcnt(0)
	s_barrier
	v_mfma_f32_16x16x32_f16 v[64:67], v[176:179], v[196:199], v[64:67]
	v_mfma_f32_16x16x32_f16 v[48:51], v[176:179], v[200:203], v[48:51]
	v_mfma_f32_16x16x32_f16 v[30:33], v[176:179], v[204:207], v[30:33]
	v_mfma_f32_16x16x32_f16 v[14:17], v[176:179], v[208:211], v[14:17]
	v_mfma_f32_16x16x32_f16 v[60:63], v[180:183], v[196:199], v[60:63]
	v_mfma_f32_16x16x32_f16 v[44:47], v[180:183], v[200:203], v[44:47]
	v_mfma_f32_16x16x32_f16 v[26:29], v[180:183], v[204:207], v[26:29]
	v_mfma_f32_16x16x32_f16 v[10:13], v[180:183], v[208:211], v[10:13]
	v_mfma_f32_16x16x32_f16 v[56:59], v[184:187], v[196:199], v[56:59]
	v_mfma_f32_16x16x32_f16 v[40:43], v[184:187], v[200:203], v[40:43]
	v_mfma_f32_16x16x32_f16 v[22:25], v[184:187], v[204:207], v[22:25]
	v_mfma_f32_16x16x32_f16 v[6:9], v[184:187], v[208:211], v[6:9]
	v_mfma_f32_16x16x32_f16 v[52:55], v[188:191], v[196:199], v[52:55]
	v_mfma_f32_16x16x32_f16 v[36:39], v[188:191], v[200:203], v[36:39]
	v_mfma_f32_16x16x32_f16 v[18:21], v[188:191], v[204:207], v[18:21]
	v_mfma_f32_16x16x32_f16 v[2:5], v[188:191], v[208:211], v[2:5]
	s_branch .LBB0_142

.Lg3_loop:
	s_add_i32 s49, s48, 1
	s_cmp_ge_i32 s49, s3
	s_cbranch_scc1 .Lg3_cold
	s_add_i32 s48, s48, 2
	s_cmp_ge_i32 s48, s3
	s_cbranch_scc1 .Lg3_warm
	v_add_u32_e32 v246, v227, v228
	v_add_u32_e32 v247, v227, v231
	v_lshlrev_b32_e32 v246, 1, v246
	v_lshlrev_b32_e32 v247, 1, v247
	v_add_u32_e32 v248, 0x20000, v246
	v_add_u32_e32 v249, 0x40000, v246
	v_add_u32_e32 v250, 0x60000, v246
	v_add_u32_e32 v251, 0x20000, v247
	v_add_u32_e32 v252, 0x40000, v247
	v_add_u32_e32 v253, 0x60000, v247
	s_waitcnt lgkmcnt(7)
	v_mfma_f32_16x16x32_f16 v[148:151], v[176:179], v[164:167], v[148:151]
	v_mfma_f32_16x16x32_f16 v[112:115], v[176:179], v[168:171], v[112:115]
	v_mfma_f32_16x16x32_f16 v[96:99], v[176:179], v[172:175], v[96:99]
	v_mfma_f32_16x16x32_f16 v[80:83], v[176:179], v[192:195], v[80:83]
	s_waitcnt vmcnt(7)
	ds_write_b128 v254, v[124:127]
	global_load_dwordx4 v[124:127], v246, s[30:31] offset:256
	s_waitcnt lgkmcnt(7)
	v_mfma_f32_16x16x32_f16 v[128:131], v[180:183], v[164:167], v[128:131]
	v_mfma_f32_16x16x32_f16 v[108:111], v[180:183], v[168:171], v[108:111]
	v_mfma_f32_16x16x32_f16 v[92:95], v[180:183], v[172:175], v[92:95]
	v_mfma_f32_16x16x32_f16 v[76:79], v[180:183], v[192:195], v[76:79]
	s_waitcnt vmcnt(7)
	ds_write_b128 v254, v[132:135] offset:1024
	global_load_dwordx4 v[132:135], v248, s[30:31] offset:256
	s_waitcnt lgkmcnt(7)
	v_mfma_f32_16x16x32_f16 v[120:123], v[184:187], v[164:167], v[120:123]
	v_mfma_f32_16x16x32_f16 v[104:107], v[184:187], v[168:171], v[104:107]
	v_mfma_f32_16x16x32_f16 v[88:91], v[184:187], v[172:175], v[88:91]
	v_mfma_f32_16x16x32_f16 v[72:75], v[184:187], v[192:195], v[72:75]
	s_waitcnt vmcnt(7)
	ds_write_b128 v254, v[136:139] offset:2048
	global_load_dwordx4 v[136:139], v249, s[30:31] offset:256
	s_waitcnt lgkmcnt(7)
	v_mfma_f32_16x16x32_f16 v[116:119], v[188:191], v[164:167], v[116:119]
	v_mfma_f32_16x16x32_f16 v[100:103], v[188:191], v[168:171], v[100:103]
	v_mfma_f32_16x16x32_f16 v[84:87], v[188:191], v[172:175], v[84:87]
	v_mfma_f32_16x16x32_f16 v[68:71], v[188:191], v[192:195], v[68:71]
	s_waitcnt vmcnt(7)
	ds_write_b128 v254, v[140:143] offset:3072
	global_load_dwordx4 v[140:143], v250, s[30:31] offset:256
	ds_read_b128 v[164:167], v239
	ds_read_b128 v[168:171], v239 offset:256
	ds_read_b128 v[172:175], v239 offset:512
	ds_read_b128 v[192:195], v239 offset:768
	s_waitcnt lgkmcnt(11)
	v_mfma_f32_16x16x32_f16 v[64:67], v[176:179], v[196:199], v[64:67]
	s_waitcnt lgkmcnt(10)
	v_mfma_f32_16x16x32_f16 v[48:51], v[176:179], v[200:203], v[48:51]
	s_waitcnt lgkmcnt(9)
	v_mfma_f32_16x16x32_f16 v[30:33], v[176:179], v[204:207], v[30:33]
	s_waitcnt lgkmcnt(8)
	v_mfma_f32_16x16x32_f16 v[14:17], v[176:179], v[208:211], v[14:17]
	ds_read_b128 v[176:179], v237
	s_waitcnt vmcnt(7)
	ds_write_b128 v255, v[144:147]
	global_load_dwordx4 v[144:147], v247, s[38:39] offset:256
	v_mfma_f32_16x16x32_f16 v[60:63], v[180:183], v[196:199], v[60:63]
	v_mfma_f32_16x16x32_f16 v[44:47], v[180:183], v[200:203], v[44:47]
	v_mfma_f32_16x16x32_f16 v[26:29], v[180:183], v[204:207], v[26:29]
	v_mfma_f32_16x16x32_f16 v[10:13], v[180:183], v[208:211], v[10:13]
	ds_read_b128 v[180:183], v237 offset:256
	s_waitcnt vmcnt(7)
	ds_write_b128 v255, v[152:155] offset:1024
	global_load_dwordx4 v[152:155], v251, s[38:39] offset:256
	v_mfma_f32_16x16x32_f16 v[56:59], v[184:187], v[196:199], v[56:59]
	v_mfma_f32_16x16x32_f16 v[40:43], v[184:187], v[200:203], v[40:43]
	v_mfma_f32_16x16x32_f16 v[22:25], v[184:187], v[204:207], v[22:25]
	v_mfma_f32_16x16x32_f16 v[6:9], v[184:187], v[208:211], v[6:9]
	ds_read_b128 v[184:187], v237 offset:512
	s_waitcnt vmcnt(7)
	ds_write_b128 v255, v[156:159] offset:2048
	global_load_dwordx4 v[156:159], v252, s[38:39] offset:256
	v_mfma_f32_16x16x32_f16 v[52:55], v[188:191], v[196:199], v[52:55]
	v_mfma_f32_16x16x32_f16 v[36:39], v[188:191], v[200:203], v[36:39]
	v_mfma_f32_16x16x32_f16 v[18:21], v[188:191], v[204:207], v[18:21]
	v_mfma_f32_16x16x32_f16 v[2:5], v[188:191], v[208:211], v[2:5]
	ds_read_b128 v[188:191], v237 offset:768
	s_waitcnt vmcnt(7)
	ds_write_b128 v255, v[160:163] offset:3072
	global_load_dwordx4 v[160:163], v253, s[38:39] offset:256
	ds_read_b128 v[196:199], v239 offset:1024
	ds_read_b128 v[200:203], v239 offset:1280
	ds_read_b128 v[204:207], v239 offset:1536
	ds_read_b128 v[208:211], v239 offset:1792
	s_waitcnt lgkmcnt(11)
	v_mfma_f32_16x16x32_f16 v[148:151], v[176:179], v[164:167], v[148:151]
	v_mfma_f32_16x16x32_f16 v[112:115], v[176:179], v[168:171], v[112:115]
	v_mfma_f32_16x16x32_f16 v[96:99], v[176:179], v[172:175], v[96:99]
	v_mfma_f32_16x16x32_f16 v[80:83], v[176:179], v[192:195], v[80:83]
	s_waitcnt lgkmcnt(9)
	v_mfma_f32_16x16x32_f16 v[128:131], v[180:183], v[164:167], v[128:131]
	v_mfma_f32_16x16x32_f16 v[108:111], v[180:183], v[168:171], v[108:111]
	v_mfma_f32_16x16x32_f16 v[92:95], v[180:183], v[172:175], v[92:95]
	v_mfma_f32_16x16x32_f16 v[76:79], v[180:183], v[192:195], v[76:79]
	s_waitcnt lgkmcnt(7)
	v_mfma_f32_16x16x32_f16 v[120:123], v[184:187], v[164:167], v[120:123]
	v_mfma_f32_16x16x32_f16 v[104:107], v[184:187], v[168:171], v[104:107]
	v_mfma_f32_16x16x32_f16 v[88:91], v[184:187], v[172:175], v[88:91]
	v_mfma_f32_16x16x32_f16 v[72:75], v[184:187], v[192:195], v[72:75]
	s_waitcnt lgkmcnt(5)
	v_mfma_f32_16x16x32_f16 v[116:119], v[188:191], v[164:167], v[116:119]
	v_mfma_f32_16x16x32_f16 v[100:103], v[188:191], v[168:171], v[100:103]
	v_mfma_f32_16x16x32_f16 v[84:87], v[188:191], v[172:175], v[84:87]
	v_mfma_f32_16x16x32_f16 v[68:71], v[188:191], v[192:195], v[68:71]
	s_waitcnt lgkmcnt(0)
	s_barrier
	ds_read_b128 v[164:167], v238
	ds_read_b128 v[168:171], v238 offset:256
	ds_read_b128 v[172:175], v238 offset:512
	ds_read_b128 v[192:195], v238 offset:768
	v_mfma_f32_16x16x32_f16 v[64:67], v[176:179], v[196:199], v[64:67]
	v_mfma_f32_16x16x32_f16 v[48:51], v[176:179], v[200:203], v[48:51]
	v_mfma_f32_16x16x32_f16 v[30:33], v[176:179], v[204:207], v[30:33]
	v_mfma_f32_16x16x32_f16 v[14:17], v[176:179], v[208:211], v[14:17]
	ds_read_b128 v[176:179], v236
	v_mfma_f32_16x16x32_f16 v[60:63], v[180:183], v[196:199], v[60:63]
	v_mfma_f32_16x16x32_f16 v[44:47], v[180:183], v[200:203], v[44:47]
	v_mfma_f32_16x16x32_f16 v[26:29], v[180:183], v[204:207], v[26:29]
	v_mfma_f32_16x16x32_f16 v[10:13], v[180:183], v[208:211], v[10:13]
	ds_read_b128 v[180:183], v236 offset:256
	v_mfma_f32_16x16x32_f16 v[56:59], v[184:187], v[196:199], v[56:59]
	v_mfma_f32_16x16x32_f16 v[40:43], v[184:187], v[200:203], v[40:43]
	v_mfma_f32_16x16x32_f16 v[22:25], v[184:187], v[204:207], v[22:25]
	v_mfma_f32_16x16x32_f16 v[6:9], v[184:187], v[208:211], v[6:9]
	ds_read_b128 v[184:187], v236 offset:512
	v_mfma_f32_16x16x32_f16 v[52:55], v[188:191], v[196:199], v[52:55]
	v_mfma_f32_16x16x32_f16 v[36:39], v[188:191], v[200:203], v[36:39]
	v_mfma_f32_16x16x32_f16 v[18:21], v[188:191], v[204:207], v[18:21]
	v_mfma_f32_16x16x32_f16 v[2:5], v[188:191], v[208:211], v[2:5]
	ds_read_b128 v[188:191], v236 offset:768
	ds_read_b128 v[196:199], v238 offset:1024
	ds_read_b128 v[200:203], v238 offset:1280
	ds_read_b128 v[204:207], v238 offset:1536
	ds_read_b128 v[208:211], v238 offset:1792
	v_xor_b32_e32 v239, 0x8000, v239
	v_xor_b32_e32 v237, 0x8000, v237
	v_xor_b32_e32 v254, 0x8000, v254
	v_xor_b32_e32 v255, 0x8000, v255
	v_xor_b32_e32 v236, 0x8000, v236
	v_xor_b32_e32 v238, 0x8000, v238
	s_addk_i32 s47, 0x800
	v_add_u32_e32 v231, 64, v231
	v_add_u32_e32 v228, 64, v228
	s_mov_b32 s48, s49
	s_branch .Lg3_loop
.Lg3_warm:
	s_waitcnt lgkmcnt(7)
	v_mfma_f32_16x16x32_f16 v[148:151], v[176:179], v[164:167], v[148:151]
	v_mfma_f32_16x16x32_f16 v[112:115], v[176:179], v[168:171], v[112:115]
	v_mfma_f32_16x16x32_f16 v[96:99], v[176:179], v[172:175], v[96:99]
	v_mfma_f32_16x16x32_f16 v[80:83], v[176:179], v[192:195], v[80:83]
	s_waitcnt vmcnt(7)
	ds_write_b128 v254, v[124:127]
	s_waitcnt lgkmcnt(7)
	v_mfma_f32_16x16x32_f16 v[128:131], v[180:183], v[164:167], v[128:131]
	v_mfma_f32_16x16x32_f16 v[108:111], v[180:183], v[168:171], v[108:111]
	v_mfma_f32_16x16x32_f16 v[92:95], v[180:183], v[172:175], v[92:95]
	v_mfma_f32_16x16x32_f16 v[76:79], v[180:183], v[192:195], v[76:79]
	s_waitcnt vmcnt(6)
	ds_write_b128 v254, v[132:135] offset:1024
	s_waitcnt lgkmcnt(7)
	v_mfma_f32_16x16x32_f16 v[120:123], v[184:187], v[164:167], v[120:123]
	v_mfma_f32_16x16x32_f16 v[104:107], v[184:187], v[168:171], v[104:107]
	v_mfma_f32_16x16x32_f16 v[88:91], v[184:187], v[172:175], v[88:91]
	v_mfma_f32_16x16x32_f16 v[72:75], v[184:187], v[192:195], v[72:75]
	s_waitcnt vmcnt(5)
	ds_write_b128 v254, v[136:139] offset:2048
	s_waitcnt lgkmcnt(7)
	v_mfma_f32_16x16x32_f16 v[116:119], v[188:191], v[164:167], v[116:119]
	v_mfma_f32_16x16x32_f16 v[100:103], v[188:191], v[168:171], v[100:103]
	v_mfma_f32_16x16x32_f16 v[84:87], v[188:191], v[172:175], v[84:87]
	v_mfma_f32_16x16x32_f16 v[68:71], v[188:191], v[192:195], v[68:71]
	s_waitcnt vmcnt(4)
	ds_write_b128 v254, v[140:143] offset:3072
	ds_read_b128 v[164:167], v239
	ds_read_b128 v[168:171], v239 offset:256
	ds_read_b128 v[172:175], v239 offset:512
	ds_read_b128 v[192:195], v239 offset:768
	s_waitcnt lgkmcnt(11)
	v_mfma_f32_16x16x32_f16 v[64:67], v[176:179], v[196:199], v[64:67]
	s_waitcnt lgkmcnt(10)
	v_mfma_f32_16x16x32_f16 v[48:51], v[176:179], v[200:203], v[48:51]
	s_waitcnt lgkmcnt(9)
	v_mfma_f32_16x16x32_f16 v[30:33], v[176:179], v[204:207], v[30:33]
	s_waitcnt lgkmcnt(8)
	v_mfma_f32_16x16x32_f16 v[14:17], v[176:179], v[208:211], v[14:17]
	ds_read_b128 v[176:179], v237
	s_waitcnt vmcnt(3)
	ds_write_b128 v255, v[144:147]
	v_mfma_f32_16x16x32_f16 v[60:63], v[180:183], v[196:199], v[60:63]
	v_mfma_f32_16x16x32_f16 v[44:47], v[180:183], v[200:203], v[44:47]
	v_mfma_f32_16x16x32_f16 v[26:29], v[180:183], v[204:207], v[26:29]
	v_mfma_f32_16x16x32_f16 v[10:13], v[180:183], v[208:211], v[10:13]
	ds_read_b128 v[180:183], v237 offset:256
	s_waitcnt vmcnt(2)
	ds_write_b128 v255, v[152:155] offset:1024
	v_mfma_f32_16x16x32_f16 v[56:59], v[184:187], v[196:199], v[56:59]
	v_mfma_f32_16x16x32_f16 v[40:43], v[184:187], v[200:203], v[40:43]
	v_mfma_f32_16x16x32_f16 v[22:25], v[184:187], v[204:207], v[22:25]
	v_mfma_f32_16x16x32_f16 v[6:9], v[184:187], v[208:211], v[6:9]
	ds_read_b128 v[184:187], v237 offset:512
	s_waitcnt vmcnt(1)
	ds_write_b128 v255, v[156:159] offset:2048
	v_mfma_f32_16x16x32_f16 v[52:55], v[188:191], v[196:199], v[52:55]
	v_mfma_f32_16x16x32_f16 v[36:39], v[188:191], v[200:203], v[36:39]
	v_mfma_f32_16x16x32_f16 v[18:21], v[188:191], v[204:207], v[18:21]
	v_mfma_f32_16x16x32_f16 v[2:5], v[188:191], v[208:211], v[2:5]
	ds_read_b128 v[188:191], v237 offset:768
	s_waitcnt vmcnt(0)
	ds_write_b128 v255, v[160:163] offset:3072
	ds_read_b128 v[196:199], v239 offset:1024
	ds_read_b128 v[200:203], v239 offset:1280
	ds_read_b128 v[204:207], v239 offset:1536
	ds_read_b128 v[208:211], v239 offset:1792
	s_waitcnt lgkmcnt(11)
	v_mfma_f32_16x16x32_f16 v[148:151], v[176:179], v[164:167], v[148:151]
	v_mfma_f32_16x16x32_f16 v[112:115], v[176:179], v[168:171], v[112:115]
	v_mfma_f32_16x16x32_f16 v[96:99], v[176:179], v[172:175], v[96:99]
	v_mfma_f32_16x16x32_f16 v[80:83], v[176:179], v[192:195], v[80:83]
	s_waitcnt lgkmcnt(9)
	v_mfma_f32_16x16x32_f16 v[128:131], v[180:183], v[164:167], v[128:131]
	v_mfma_f32_16x16x32_f16 v[108:111], v[180:183], v[168:171], v[108:111]
	v_mfma_f32_16x16x32_f16 v[92:95], v[180:183], v[172:175], v[92:95]
	v_mfma_f32_16x16x32_f16 v[76:79], v[180:183], v[192:195], v[76:79]
	s_waitcnt lgkmcnt(7)
	v_mfma_f32_16x16x32_f16 v[120:123], v[184:187], v[164:167], v[120:123]
	v_mfma_f32_16x16x32_f16 v[104:107], v[184:187], v[168:171], v[104:107]
	v_mfma_f32_16x16x32_f16 v[88:91], v[184:187], v[172:175], v[88:91]
	v_mfma_f32_16x16x32_f16 v[72:75], v[184:187], v[192:195], v[72:75]
	s_waitcnt lgkmcnt(5)
	v_mfma_f32_16x16x32_f16 v[116:119], v[188:191], v[164:167], v[116:119]
	v_mfma_f32_16x16x32_f16 v[100:103], v[188:191], v[168:171], v[100:103]
	v_mfma_f32_16x16x32_f16 v[84:87], v[188:191], v[172:175], v[84:87]
	v_mfma_f32_16x16x32_f16 v[68:71], v[188:191], v[192:195], v[68:71]
	s_waitcnt lgkmcnt(0)
	s_barrier
	ds_read_b128 v[164:167], v238
	ds_read_b128 v[168:171], v238 offset:256
	ds_read_b128 v[172:175], v238 offset:512
	ds_read_b128 v[192:195], v238 offset:768
	v_mfma_f32_16x16x32_f16 v[64:67], v[176:179], v[196:199], v[64:67]
	v_mfma_f32_16x16x32_f16 v[48:51], v[176:179], v[200:203], v[48:51]
	v_mfma_f32_16x16x32_f16 v[30:33], v[176:179], v[204:207], v[30:33]
	v_mfma_f32_16x16x32_f16 v[14:17], v[176:179], v[208:211], v[14:17]
	ds_read_b128 v[176:179], v236
	v_mfma_f32_16x16x32_f16 v[60:63], v[180:183], v[196:199], v[60:63]
	v_mfma_f32_16x16x32_f16 v[44:47], v[180:183], v[200:203], v[44:47]
	v_mfma_f32_16x16x32_f16 v[26:29], v[180:183], v[204:207], v[26:29]
	v_mfma_f32_16x16x32_f16 v[10:13], v[180:183], v[208:211], v[10:13]
	ds_read_b128 v[180:183], v236 offset:256
	v_mfma_f32_16x16x32_f16 v[56:59], v[184:187], v[196:199], v[56:59]
	v_mfma_f32_16x16x32_f16 v[40:43], v[184:187], v[200:203], v[40:43]
	v_mfma_f32_16x16x32_f16 v[22:25], v[184:187], v[204:207], v[22:25]
	v_mfma_f32_16x16x32_f16 v[6:9], v[184:187], v[208:211], v[6:9]
	ds_read_b128 v[184:187], v236 offset:512
	v_mfma_f32_16x16x32_f16 v[52:55], v[188:191], v[196:199], v[52:55]
	v_mfma_f32_16x16x32_f16 v[36:39], v[188:191], v[200:203], v[36:39]
	v_mfma_f32_16x16x32_f16 v[18:21], v[188:191], v[204:207], v[18:21]
	v_mfma_f32_16x16x32_f16 v[2:5], v[188:191], v[208:211], v[2:5]
	ds_read_b128 v[188:191], v236 offset:768
	ds_read_b128 v[196:199], v238 offset:1024
	ds_read_b128 v[200:203], v238 offset:1280
	ds_read_b128 v[204:207], v238 offset:1536
	ds_read_b128 v[208:211], v238 offset:1792
	v_xor_b32_e32 v239, 0x8000, v239
	v_xor_b32_e32 v237, 0x8000, v237
	v_xor_b32_e32 v254, 0x8000, v254
	v_xor_b32_e32 v255, 0x8000, v255
	v_xor_b32_e32 v236, 0x8000, v236
	v_xor_b32_e32 v238, 0x8000, v238
	s_addk_i32 s47, 0x800
	v_add_u32_e32 v231, 64, v231
	v_add_u32_e32 v228, 64, v228
	s_mov_b32 s48, s49
	s_branch .Lg3_loop

.LBB0_241:
	v_mov_b32_e32 v12, v1
	s_lshl_b32 s24, s58, 10
	v_ashrrev_i32_e32 v14, 3, v12
	v_lshlrev_b32_e32 v2, 1, v14
	v_and_b32_e32 v15, 7, v12
	v_and_b32_e32 v10, 24, v2
	v_lshrrev_b32_e32 v2, 2, v14
	v_lshlrev_b32_e32 v124, 3, v15
	v_and_b32_e32 v11, 4, v2
	v_and_b32_e32 v13, 35, v14
	v_lshlrev_b32_e32 v125, 10, v14
	v_or3_b32 v3, v13, v10, v11
	v_or_b32_e32 v2, v125, v124
	v_lshl_or_b32 v16, v3, 10, v124
	v_mov_b32_e32 v3, v34
	v_add_u32_e32 v6, 0x10000, v2
	v_mov_b32_e32 v7, v34
	s_add_i32 s38, s55, s24
	s_mov_b32 s42, 16
	v_lshl_add_u64 v[4:5], v[2:3], 1, s[40:41]
	v_lshl_add_u64 v[6:7], v[6:7], 1, s[40:41]
	s_ashr_i32 s39, s38, 31
	global_load_dwordx4 v[36:39], v[4:5], off
	global_load_dwordx4 v[40:43], v[6:7], off
	v_add_u32_e32 v6, 0x20000, v2
	v_mov_b32_e32 v7, v34
	v_add_u32_e32 v8, 0x30000, v2
	v_mov_b32_e32 v9, v34
	s_lshl_b64 s[38:39], s[38:39], 11
	v_lshl_add_u64 v[6:7], v[6:7], 1, s[40:41]
	v_lshl_add_u64 v[8:9], v[8:9], 1, s[40:41]
	s_add_u32 s38, s2, s38
	global_load_dwordx4 v[52:55], v[6:7], off
	global_load_dwordx4 v[56:59], v[8:9], off
	v_lshlrev_b32_e32 v8, 1, v16
	s_addc_u32 s39, s3, s39
	v_or_b32_e32 v6, 0x20000, v8
	global_load_dwordx4 v[68:71], v8, s[38:39]
	global_load_dwordx4 v[76:79], v6, s[38:39]
	v_bitop3_b32 v3, v14, v12, 7 bitop3:0x78
	v_lshlrev_b32_e32 v7, 12, v15
	v_lshlrev_b32_e32 v9, 11, v15
	v_lshlrev_b32_e32 v3, 4, v3
	s_add_i32 s59, 0, 0x10000
	v_add3_u32 v126, 0, v7, v3
	v_add3_u32 v127, s59, v9, v3
	s_cmp_lt_i32 s42, 2
	s_waitcnt vmcnt(5)
	ds_write_b128 v126, v[36:39]
	s_waitcnt vmcnt(4)
	ds_write_b128 v126, v[40:43] offset:1024
	s_waitcnt vmcnt(3)
	ds_write_b128 v126, v[52:55] offset:2048
	s_waitcnt vmcnt(2)
	ds_write_b128 v126, v[56:59] offset:3072
	s_waitcnt vmcnt(1)
	ds_write_b128 v127, v[68:71]
	s_waitcnt vmcnt(0)
	ds_write_b128 v127, v[76:79] offset:1024
	s_cbranch_scc1 .LBB0_243
	v_add_u32_e32 v16, 0x20040, v2
	v_mov_b32_e32 v17, v34
	v_mov_b32_e32 v9, v34
	v_mov_b32_e32 v7, v34
	v_add_u32_e32 v14, 0x10040, v2
	v_mov_b32_e32 v15, v34
	v_lshl_add_u64 v[16:17], v[16:17], 1, s[40:41]
	v_add_u32_e32 v2, 0x30040, v2
	v_mov_b32_e32 v3, v34
	v_lshl_add_u64 v[8:9], s[38:39], 0, v[8:9]
	v_lshl_add_u64 v[6:7], s[38:39], 0, v[6:7]
	v_lshl_add_u64 v[14:15], v[14:15], 1, s[40:41]
	v_lshl_add_u64 v[2:3], v[2:3], 1, s[40:41]
	global_load_dwordx4 v[36:39], v[4:5], off offset:128
	global_load_dwordx4 v[40:43], v[14:15], off
	global_load_dwordx4 v[52:55], v[16:17], off
	global_load_dwordx4 v[56:59], v[2:3], off
	global_load_dwordx4 v[68:71], v[8:9], off offset:128
	global_load_dwordx4 v[76:79], v[6:7], off offset:128

.LBB0_245:
	s_and_b32 s45, s43, 1
	s_lshl_b32 s44, s45, 15
	s_add_i32 s44, s44, 0
	v_add_u32_e32 v108, s44, v128
	v_add_u32_e32 v109, s44, v129
	s_lshl_b32 s44, s45, 14
	s_add_i32 s44, s44, 0
	s_add_i32 s44, s44, 0x10000
	v_add_u32_e32 v84, s44, v130
	v_add3_u32 v104, v84, v134, v135
	v_add3_u32 v120, v108, v133, v135
	ds_read_b128 v[84:87], v104
	ds_read_b128 v[88:91], v104 offset:256
	ds_read_b128 v[100:103], v104 offset:512
	ds_read_b128 v[104:107], v104 offset:768
	v_add3_u32 v138, v109, v133, v136
	ds_read_b128 v[108:111], v120
	ds_read_b128 v[112:115], v120 offset:256
	ds_read_b128 v[116:119], v120 offset:512
	ds_read_b128 v[120:123], v120 offset:768
	v_add_u32_e32 v137, s44, v131
	s_waitcnt lgkmcnt(3)
	v_mfma_f32_16x16x32_f16 v[96:99], v[84:87], v[108:111], v[96:99]
	v_mfma_f32_16x16x32_f16 v[92:95], v[88:91], v[108:111], v[92:95]
	v_mfma_f32_16x16x32_f16 v[80:83], v[100:103], v[108:111], v[80:83]
	v_mfma_f32_16x16x32_f16 v[72:75], v[104:107], v[108:111], v[72:75]
	s_waitcnt lgkmcnt(2)
	v_mfma_f32_16x16x32_f16 v[64:67], v[84:87], v[112:115], v[64:67]
	v_mfma_f32_16x16x32_f16 v[60:63], v[88:91], v[112:115], v[60:63]
	v_mfma_f32_16x16x32_f16 v[48:51], v[100:103], v[112:115], v[48:51]
	v_mfma_f32_16x16x32_f16 v[44:47], v[104:107], v[112:115], v[44:47]
	s_waitcnt lgkmcnt(1)
	v_mfma_f32_16x16x32_f16 v[30:33], v[84:87], v[116:119], v[30:33]
	v_mfma_f32_16x16x32_f16 v[26:29], v[88:91], v[116:119], v[26:29]
	v_mfma_f32_16x16x32_f16 v[22:25], v[100:103], v[116:119], v[22:25]
	v_mfma_f32_16x16x32_f16 v[18:21], v[104:107], v[116:119], v[18:21]
	s_waitcnt lgkmcnt(0)
	v_mfma_f32_16x16x32_f16 v[14:17], v[84:87], v[120:123], v[14:17]
	v_add3_u32 v84, v137, v134, v136
	v_mfma_f32_16x16x32_f16 v[10:13], v[88:91], v[120:123], v[10:13]
	v_mfma_f32_16x16x32_f16 v[2:5], v[100:103], v[120:123], v[2:5]
	v_mfma_f32_16x16x32_f16 v[6:9], v[104:107], v[120:123], v[6:9]
	ds_read_b128 v[104:107], v84
	ds_read_b128 v[108:111], v84 offset:256
	ds_read_b128 v[100:103], v84 offset:512
	ds_read_b128 v[84:87], v84 offset:768
	ds_read_b128 v[120:123], v138
	ds_read_b128 v[116:119], v138 offset:256
	ds_read_b128 v[112:115], v138 offset:512
	ds_read_b128 v[88:91], v138 offset:768
	s_add_i32 s44, s43, 1
	s_cmp_ge_i32 s44, s42
	s_cbranch_scc1 .Ls1_cold
	s_xor_b32 s45, s45, 1
	v_lshl_add_u32 v254, s45, 15, v126
	v_lshl_add_u32 v255, s45, 14, v127
	s_add_i32 s43, s43, 2
	s_cmp_ge_i32 s43, s42
	s_cbranch_scc1 .Ls1_warm
	v_add_u32_e32 v246, v124, v125
	v_add_u32_e32 v247, v124, v132
	v_lshlrev_b32_e32 v246, 1, v246
	v_lshlrev_b32_e32 v247, 1, v247
	v_add_u32_e32 v248, 0x20000, v246
	v_add_u32_e32 v249, 0x40000, v246
	v_add_u32_e32 v250, 0x60000, v246
	v_add_u32_e32 v251, 0x20000, v247
	s_waitcnt vmcnt(5)
	ds_write_b128 v254, v[36:39]
	global_load_dwordx4 v[36:39], v246, s[40:41] offset:256
	s_waitcnt vmcnt(5)
	ds_write_b128 v254, v[40:43] offset:1024
	global_load_dwordx4 v[40:43], v248, s[40:41] offset:256
	s_waitcnt lgkmcnt(5)
	v_mfma_f32_16x16x32_f16 v[96:99], v[104:107], v[120:123], v[96:99]
	v_add_u32_e32 v132, 64, v132
	v_add_u32_e32 v125, 64, v125
	s_cmp_lg_u32 s42, s44
	v_mfma_f32_16x16x32_f16 v[92:95], v[108:111], v[120:123], v[92:95]
	v_mfma_f32_16x16x32_f16 v[80:83], v[100:103], v[120:123], v[80:83]
	v_mfma_f32_16x16x32_f16 v[72:75], v[84:87], v[120:123], v[72:75]
	s_waitcnt vmcnt(5)
	ds_write_b128 v254, v[52:55] offset:2048
	global_load_dwordx4 v[52:55], v249, s[40:41] offset:256
	s_waitcnt vmcnt(5)
	ds_write_b128 v254, v[56:59] offset:3072
	global_load_dwordx4 v[56:59], v250, s[40:41] offset:256
	s_waitcnt lgkmcnt(6)
	v_mfma_f32_16x16x32_f16 v[64:67], v[104:107], v[116:119], v[64:67]
	v_mfma_f32_16x16x32_f16 v[60:63], v[108:111], v[116:119], v[60:63]
	v_mfma_f32_16x16x32_f16 v[48:51], v[100:103], v[116:119], v[48:51]
	v_mfma_f32_16x16x32_f16 v[44:47], v[84:87], v[116:119], v[44:47]
	s_waitcnt vmcnt(5)
	ds_write_b128 v255, v[68:71]
	global_load_dwordx4 v[68:71], v247, s[38:39] offset:256
	s_waitcnt lgkmcnt(6)
	v_mfma_f32_16x16x32_f16 v[30:33], v[104:107], v[112:115], v[30:33]
	v_mfma_f32_16x16x32_f16 v[26:29], v[108:111], v[112:115], v[26:29]
	v_mfma_f32_16x16x32_f16 v[22:25], v[100:103], v[112:115], v[22:25]
	v_mfma_f32_16x16x32_f16 v[18:21], v[84:87], v[112:115], v[18:21]
	s_waitcnt vmcnt(5)
	ds_write_b128 v255, v[76:79] offset:1024
	global_load_dwordx4 v[76:79], v251, s[38:39] offset:256
	s_waitcnt lgkmcnt(6)
	v_mfma_f32_16x16x32_f16 v[14:17], v[104:107], v[88:91], v[14:17]
	v_mfma_f32_16x16x32_f16 v[10:13], v[108:111], v[88:91], v[10:13]
	v_mfma_f32_16x16x32_f16 v[2:5], v[100:103], v[88:91], v[2:5]
	v_mfma_f32_16x16x32_f16 v[6:9], v[84:87], v[88:91], v[6:9]
	s_waitcnt lgkmcnt(0)
	s_barrier
.Ls1_tail:
	s_cbranch_scc0 .LBB0_251
	s_mov_b32 s43, s44
	s_branch .LBB0_245
.Ls1_cold:
	s_waitcnt lgkmcnt(3)
	v_mfma_f32_16x16x32_f16 v[96:99], v[104:107], v[120:123], v[96:99]
	v_add_u32_e32 v132, 64, v132
	v_add_u32_e32 v125, 64, v125
	s_cmp_lg_u32 s42, s44
	v_mfma_f32_16x16x32_f16 v[92:95], v[108:111], v[120:123], v[92:95]
	s_waitcnt lgkmcnt(0)
	s_barrier
	v_mfma_f32_16x16x32_f16 v[80:83], v[100:103], v[120:123], v[80:83]
	v_mfma_f32_16x16x32_f16 v[72:75], v[84:87], v[120:123], v[72:75]
	v_mfma_f32_16x16x32_f16 v[64:67], v[104:107], v[116:119], v[64:67]
	v_mfma_f32_16x16x32_f16 v[60:63], v[108:111], v[116:119], v[60:63]
	v_mfma_f32_16x16x32_f16 v[48:51], v[100:103], v[116:119], v[48:51]
	v_mfma_f32_16x16x32_f16 v[44:47], v[84:87], v[116:119], v[44:47]
	v_mfma_f32_16x16x32_f16 v[30:33], v[104:107], v[112:115], v[30:33]
	v_mfma_f32_16x16x32_f16 v[26:29], v[108:111], v[112:115], v[26:29]
	v_mfma_f32_16x16x32_f16 v[22:25], v[100:103], v[112:115], v[22:25]
	v_mfma_f32_16x16x32_f16 v[18:21], v[84:87], v[112:115], v[18:21]
	v_mfma_f32_16x16x32_f16 v[14:17], v[104:107], v[88:91], v[14:17]
	v_mfma_f32_16x16x32_f16 v[10:13], v[108:111], v[88:91], v[10:13]
	v_mfma_f32_16x16x32_f16 v[2:5], v[100:103], v[88:91], v[2:5]
	v_mfma_f32_16x16x32_f16 v[6:9], v[84:87], v[88:91], v[6:9]
	s_branch .Ls1_tail
.Ls1_warm:
	s_waitcnt vmcnt(5)
	ds_write_b128 v254, v[36:39]
	s_waitcnt vmcnt(4)
	ds_write_b128 v254, v[40:43] offset:1024
	s_waitcnt vmcnt(3)
	ds_write_b128 v254, v[52:55] offset:2048
	s_waitcnt vmcnt(2)
	ds_write_b128 v254, v[56:59] offset:3072
	s_waitcnt vmcnt(1)
	ds_write_b128 v255, v[68:71]
	s_waitcnt vmcnt(0)
	ds_write_b128 v255, v[76:79] offset:1024
	s_waitcnt lgkmcnt(9)
	v_mfma_f32_16x16x32_f16 v[96:99], v[104:107], v[120:123], v[96:99]
	v_add_u32_e32 v132, 64, v132
	v_add_u32_e32 v125, 64, v125
	s_cmp_lg_u32 s42, s44
	v_mfma_f32_16x16x32_f16 v[92:95], v[108:111], v[120:123], v[92:95]
	s_waitcnt lgkmcnt(0)
	s_barrier
	v_mfma_f32_16x16x32_f16 v[80:83], v[100:103], v[120:123], v[80:83]
	v_mfma_f32_16x16x32_f16 v[72:75], v[84:87], v[120:123], v[72:75]
	v_mfma_f32_16x16x32_f16 v[64:67], v[104:107], v[116:119], v[64:67]
	v_mfma_f32_16x16x32_f16 v[60:63], v[108:111], v[116:119], v[60:63]
	v_mfma_f32_16x16x32_f16 v[48:51], v[100:103], v[116:119], v[48:51]
	v_mfma_f32_16x16x32_f16 v[44:47], v[84:87], v[116:119], v[44:47]
	v_mfma_f32_16x16x32_f16 v[30:33], v[104:107], v[112:115], v[30:33]
	v_mfma_f32_16x16x32_f16 v[26:29], v[108:111], v[112:115], v[26:29]
	v_mfma_f32_16x16x32_f16 v[22:25], v[100:103], v[112:115], v[22:25]
	v_mfma_f32_16x16x32_f16 v[18:21], v[84:87], v[112:115], v[18:21]
	v_mfma_f32_16x16x32_f16 v[14:17], v[104:107], v[88:91], v[14:17]
	v_mfma_f32_16x16x32_f16 v[10:13], v[108:111], v[88:91], v[10:13]
	v_mfma_f32_16x16x32_f16 v[2:5], v[100:103], v[88:91], v[2:5]
	v_mfma_f32_16x16x32_f16 v[6:9], v[84:87], v[88:91], v[6:9]
	s_branch .Ls1_tail

.LBB0_251:
	s_cmp_eq_u32 s58, 1
	s_waitcnt vmcnt(1)
	v_lshl_add_u64 v[40:41], s[24:25], 2, v[204:205]
	s_cselect_b32 s44, 0x200, 0
	s_cmp_lg_u32 s58, 0
	v_mov_b32_e32 v86, v1
	global_load_dwordx4 v[52:55], v[40:41], off offset:16
	global_load_dwordx4 v[56:59], v[40:41], off
	global_load_dwordx4 v[36:39], v[40:41], off offset:144
	s_nop 0
	global_load_dwordx4 v[40:43], v[40:41], off offset:128
	s_cselect_b64 s[42:43], -1, 0
	s_and_b64 s[38:39], s[42:43], exec
	v_ashrrev_i32_e32 v88, 3, v86
	v_lshlrev_b32_e32 v68, 1, v88
	s_cselect_b32 s38, s44, 0x400
	v_and_b32_e32 v89, 7, v86
	v_and_b32_e32 v84, 24, v68
	v_lshrrev_b32_e32 v68, 2, v88
	s_lshl_b32 s38, s38, 1
	v_lshlrev_b32_e32 v208, 3, v89
	v_and_b32_e32 v85, 4, v68
	v_and_b32_e32 v87, 35, v88
	v_mul_lo_u32 v209, v88, s88
	s_add_u32 s38, s56, s38
	v_or3_b32 v69, v87, v84, v85
	v_or_b32_e32 v68, v209, v208
	s_addc_u32 s39, s57, 0
	s_or_b32 s24, s24, s54
	v_lshl_or_b32 v90, v69, 9, v208
	v_mov_b32_e32 v69, v34
	s_waitcnt vmcnt(4)
	v_add_u32_e32 v76, 0x3e000, v68
	v_mov_b32_e32 v77, v34
	s_lshl_b64 s[44:45], s[24:25], 10
	s_mov_b32 s24, 8
	v_lshl_add_u64 v[70:71], v[68:69], 1, s[38:39]
	v_lshl_add_u64 v[76:77], v[76:77], 1, s[38:39]
	global_load_dwordx4 v[148:151], v[70:71], off
	global_load_dwordx4 v[152:155], v[76:77], off
	v_add_u32_e32 v76, 0x7c000, v68
	v_mov_b32_e32 v77, v34
	v_add_u32_e32 v78, 0xba000, v68
	v_mov_b32_e32 v79, v34
	s_add_u32 s44, s51, s44
	v_lshl_add_u64 v[76:77], v[76:77], 1, s[38:39]
	v_lshl_add_u64 v[78:79], v[78:79], 1, s[38:39]
	s_addc_u32 s45, s52, s45
	global_load_dwordx4 v[156:159], v[76:77], off
	global_load_dwordx4 v[160:163], v[78:79], off
	v_lshlrev_b32_e32 v78, 1, v90
	v_or_b32_e32 v76, 0x10000, v78
	global_load_dwordx4 v[164:167], v78, s[44:45]
	global_load_dwordx4 v[168:171], v76, s[44:45]
	v_bitop3_b32 v69, v88, v86, 7 bitop3:0x78
	v_lshlrev_b32_e32 v77, 12, v89
	v_lshlrev_b32_e32 v79, 11, v89
	v_lshlrev_b32_e32 v69, 4, v69
	v_add3_u32 v210, 0, v77, v69
	v_add3_u32 v211, s59, v79, v69
	s_cmp_lt_i32 s24, 2
	s_waitcnt vmcnt(5)
	ds_write_b128 v210, v[148:151]
	s_waitcnt vmcnt(4)
	ds_write_b128 v210, v[152:155] offset:1024
	s_waitcnt vmcnt(3)
	ds_write_b128 v210, v[156:159] offset:2048
	s_waitcnt vmcnt(2)
	ds_write_b128 v210, v[160:163] offset:3072
	s_waitcnt vmcnt(1)
	ds_write_b128 v211, v[164:167]
	s_waitcnt vmcnt(0)
	ds_write_b128 v211, v[168:171] offset:1024
	s_cbranch_scc1 .LBB0_253
	v_add_u32_e32 v90, 0x7c040, v68
	v_mov_b32_e32 v91, v34
	v_mov_b32_e32 v79, v34
	v_mov_b32_e32 v77, v34
	v_add_u32_e32 v88, 0x3e040, v68
	v_mov_b32_e32 v89, v34
	v_lshl_add_u64 v[90:91], v[90:91], 1, s[38:39]
	v_add_u32_e32 v68, 0xba040, v68
	v_mov_b32_e32 v69, v34
	v_lshl_add_u64 v[78:79], s[44:45], 0, v[78:79]
	v_lshl_add_u64 v[76:77], s[44:45], 0, v[76:77]
	v_lshl_add_u64 v[88:89], v[88:89], 1, s[38:39]
	v_lshl_add_u64 v[68:69], v[68:69], 1, s[38:39]
	global_load_dwordx4 v[148:151], v[70:71], off offset:128
	global_load_dwordx4 v[152:155], v[88:89], off
	global_load_dwordx4 v[156:159], v[90:91], off
	global_load_dwordx4 v[160:163], v[68:69], off
	global_load_dwordx4 v[164:167], v[78:79], off offset:128
	global_load_dwordx4 v[168:171], v[76:77], off offset:128

.LBB0_255:
	s_and_b32 s61, s59, 1
	s_lshl_b32 s60, s61, 15
	s_add_i32 s60, s60, 0
	v_add_u32_e32 v188, s60, v226
	v_add_u32_e32 v189, s60, v227
	s_lshl_b32 s60, s61, 14
	s_add_i32 s60, s60, 0
	s_add_i32 s60, s60, 0x10000
	v_add_u32_e32 v172, s60, v228
	v_add3_u32 v184, v172, v232, v233
	v_add3_u32 v200, v188, v231, v233
	ds_read_b128 v[172:175], v184
	ds_read_b128 v[176:179], v184 offset:256
	ds_read_b128 v[180:183], v184 offset:512
	ds_read_b128 v[184:187], v184 offset:768
	v_add3_u32 v236, v189, v231, v234
	ds_read_b128 v[188:191], v200
	ds_read_b128 v[192:195], v200 offset:256
	ds_read_b128 v[196:199], v200 offset:512
	ds_read_b128 v[200:203], v200 offset:768
	v_add_u32_e32 v235, s60, v229
	s_waitcnt lgkmcnt(3)
	v_mfma_f32_16x16x32_f16 v[144:147], v[172:175], v[188:191], v[144:147]
	v_mfma_f32_16x16x32_f16 v[140:143], v[176:179], v[188:191], v[140:143]
	v_mfma_f32_16x16x32_f16 v[136:139], v[180:183], v[188:191], v[136:139]
	v_mfma_f32_16x16x32_f16 v[132:135], v[184:187], v[188:191], v[132:135]
	s_waitcnt lgkmcnt(2)
	v_mfma_f32_16x16x32_f16 v[128:131], v[172:175], v[192:195], v[128:131]
	v_mfma_f32_16x16x32_f16 v[124:127], v[176:179], v[192:195], v[124:127]
	v_mfma_f32_16x16x32_f16 v[120:123], v[180:183], v[192:195], v[120:123]
	v_mfma_f32_16x16x32_f16 v[116:119], v[184:187], v[192:195], v[116:119]
	s_waitcnt lgkmcnt(1)
	v_mfma_f32_16x16x32_f16 v[112:115], v[172:175], v[196:199], v[112:115]
	v_mfma_f32_16x16x32_f16 v[108:111], v[176:179], v[196:199], v[108:111]
	v_mfma_f32_16x16x32_f16 v[104:107], v[180:183], v[196:199], v[104:107]
	v_mfma_f32_16x16x32_f16 v[100:103], v[184:187], v[196:199], v[100:103]
	s_waitcnt lgkmcnt(0)
	v_mfma_f32_16x16x32_f16 v[88:91], v[172:175], v[200:203], v[88:91]
	v_add3_u32 v172, v235, v232, v234
	v_mfma_f32_16x16x32_f16 v[84:87], v[176:179], v[200:203], v[84:87]
	v_mfma_f32_16x16x32_f16 v[68:71], v[180:183], v[200:203], v[68:71]
	v_mfma_f32_16x16x32_f16 v[76:79], v[184:187], v[200:203], v[76:79]
	ds_read_b128 v[184:187], v172
	ds_read_b128 v[188:191], v172 offset:256
	ds_read_b128 v[180:183], v172 offset:512
	ds_read_b128 v[172:175], v172 offset:768
	ds_read_b128 v[200:203], v236
	ds_read_b128 v[196:199], v236 offset:256
	ds_read_b128 v[192:195], v236 offset:512
	ds_read_b128 v[176:179], v236 offset:768
	s_add_i32 s60, s59, 1
	s_cmp_ge_i32 s60, s24
	s_cbranch_scc1 .Ls2_cold
	s_xor_b32 s61, s61, 1
	v_lshl_add_u32 v254, s61, 15, v210
	v_lshl_add_u32 v255, s61, 14, v211
	s_add_i32 s59, s59, 2
	s_cmp_ge_i32 s59, s24
	s_cbranch_scc1 .Ls2_warm
	v_add_u32_e32 v246, v208, v209
	v_add_u32_e32 v247, v208, v230
	v_lshlrev_b32_e32 v246, 1, v246
	v_lshlrev_b32_e32 v247, 1, v247
	v_add_u32_e32 v248, 0x7c000, v246
	v_add_u32_e32 v249, 0xf8000, v246
	v_add_u32_e32 v250, 0x174000, v246
	v_add_u32_e32 v251, 0x10000, v247
	s_waitcnt vmcnt(5)
	ds_write_b128 v254, v[148:151]
	global_load_dwordx4 v[148:151], v246, s[38:39] offset:256
	s_waitcnt vmcnt(5)
	ds_write_b128 v254, v[152:155] offset:1024
	global_load_dwordx4 v[152:155], v248, s[38:39] offset:256
	s_waitcnt lgkmcnt(5)
	v_mfma_f32_16x16x32_f16 v[144:147], v[184:187], v[200:203], v[144:147]
	v_add_u32_e32 v230, 64, v230
	v_add_u32_e32 v209, 64, v209
	s_cmp_lg_u32 s24, s60
	v_mfma_f32_16x16x32_f16 v[140:143], v[188:191], v[200:203], v[140:143]
	v_mfma_f32_16x16x32_f16 v[136:139], v[180:183], v[200:203], v[136:139]
	v_mfma_f32_16x16x32_f16 v[132:135], v[172:175], v[200:203], v[132:135]
	s_waitcnt vmcnt(5)
	ds_write_b128 v254, v[156:159] offset:2048
	global_load_dwordx4 v[156:159], v249, s[38:39] offset:256
	s_waitcnt vmcnt(5)
	ds_write_b128 v254, v[160:163] offset:3072
	global_load_dwordx4 v[160:163], v250, s[38:39] offset:256
	s_waitcnt lgkmcnt(6)
	v_mfma_f32_16x16x32_f16 v[128:131], v[184:187], v[196:199], v[128:131]
	v_mfma_f32_16x16x32_f16 v[124:127], v[188:191], v[196:199], v[124:127]
	v_mfma_f32_16x16x32_f16 v[120:123], v[180:183], v[196:199], v[120:123]
	v_mfma_f32_16x16x32_f16 v[116:119], v[172:175], v[196:199], v[116:119]
	s_waitcnt vmcnt(5)
	ds_write_b128 v255, v[164:167]
	global_load_dwordx4 v[164:167], v247, s[44:45] offset:256
	s_waitcnt lgkmcnt(6)
	v_mfma_f32_16x16x32_f16 v[112:115], v[184:187], v[192:195], v[112:115]
	v_mfma_f32_16x16x32_f16 v[108:111], v[188:191], v[192:195], v[108:111]
	v_mfma_f32_16x16x32_f16 v[104:107], v[180:183], v[192:195], v[104:107]
	v_mfma_f32_16x16x32_f16 v[100:103], v[172:175], v[192:195], v[100:103]
	s_waitcnt vmcnt(5)
	ds_write_b128 v255, v[168:171] offset:1024
	global_load_dwordx4 v[168:171], v251, s[44:45] offset:256
	s_waitcnt lgkmcnt(6)
	v_mfma_f32_16x16x32_f16 v[88:91], v[184:187], v[176:179], v[88:91]
	v_mfma_f32_16x16x32_f16 v[84:87], v[188:191], v[176:179], v[84:87]
	v_mfma_f32_16x16x32_f16 v[68:71], v[180:183], v[176:179], v[68:71]
	v_mfma_f32_16x16x32_f16 v[76:79], v[172:175], v[176:179], v[76:79]
	s_waitcnt lgkmcnt(0)
	s_barrier
.Ls2_tail:
	s_cbranch_scc0 .LBB0_261
	s_mov_b32 s59, s60
	s_branch .LBB0_255
.Ls2_cold:
	s_waitcnt lgkmcnt(3)
	v_mfma_f32_16x16x32_f16 v[144:147], v[184:187], v[200:203], v[144:147]
	v_add_u32_e32 v230, 64, v230
	v_add_u32_e32 v209, 64, v209
	s_cmp_lg_u32 s24, s60
	v_mfma_f32_16x16x32_f16 v[140:143], v[188:191], v[200:203], v[140:143]
	s_waitcnt lgkmcnt(0)
	s_barrier
	v_mfma_f32_16x16x32_f16 v[136:139], v[180:183], v[200:203], v[136:139]
	v_mfma_f32_16x16x32_f16 v[132:135], v[172:175], v[200:203], v[132:135]
	v_mfma_f32_16x16x32_f16 v[128:131], v[184:187], v[196:199], v[128:131]
	v_mfma_f32_16x16x32_f16 v[124:127], v[188:191], v[196:199], v[124:127]
	v_mfma_f32_16x16x32_f16 v[120:123], v[180:183], v[196:199], v[120:123]
	v_mfma_f32_16x16x32_f16 v[116:119], v[172:175], v[196:199], v[116:119]
	v_mfma_f32_16x16x32_f16 v[112:115], v[184:187], v[192:195], v[112:115]
	v_mfma_f32_16x16x32_f16 v[108:111], v[188:191], v[192:195], v[108:111]
	v_mfma_f32_16x16x32_f16 v[104:107], v[180:183], v[192:195], v[104:107]
	v_mfma_f32_16x16x32_f16 v[100:103], v[172:175], v[192:195], v[100:103]
	v_mfma_f32_16x16x32_f16 v[88:91], v[184:187], v[176:179], v[88:91]
	v_mfma_f32_16x16x32_f16 v[84:87], v[188:191], v[176:179], v[84:87]
	v_mfma_f32_16x16x32_f16 v[68:71], v[180:183], v[176:179], v[68:71]
	v_mfma_f32_16x16x32_f16 v[76:79], v[172:175], v[176:179], v[76:79]
	s_branch .Ls2_tail
.Ls2_warm:
	s_waitcnt vmcnt(5)
	ds_write_b128 v254, v[148:151]
	s_waitcnt vmcnt(4)
	ds_write_b128 v254, v[152:155] offset:1024
	s_waitcnt vmcnt(3)
	ds_write_b128 v254, v[156:159] offset:2048
	s_waitcnt vmcnt(2)
	ds_write_b128 v254, v[160:163] offset:3072
	s_waitcnt vmcnt(1)
	ds_write_b128 v255, v[164:167]
	s_waitcnt vmcnt(0)
	ds_write_b128 v255, v[168:171] offset:1024
	s_waitcnt lgkmcnt(9)
	v_mfma_f32_16x16x32_f16 v[144:147], v[184:187], v[200:203], v[144:147]
	v_add_u32_e32 v230, 64, v230
	v_add_u32_e32 v209, 64, v209
	s_cmp_lg_u32 s24, s60
	v_mfma_f32_16x16x32_f16 v[140:143], v[188:191], v[200:203], v[140:143]
	s_waitcnt lgkmcnt(0)
	s_barrier
	v_mfma_f32_16x16x32_f16 v[136:139], v[180:183], v[200:203], v[136:139]
	v_mfma_f32_16x16x32_f16 v[132:135], v[172:175], v[200:203], v[132:135]
	v_mfma_f32_16x16x32_f16 v[128:131], v[184:187], v[196:199], v[128:131]
	v_mfma_f32_16x16x32_f16 v[124:127], v[188:191], v[196:199], v[124:127]
	v_mfma_f32_16x16x32_f16 v[120:123], v[180:183], v[196:199], v[120:123]
	v_mfma_f32_16x16x32_f16 v[116:119], v[172:175], v[196:199], v[116:119]
	v_mfma_f32_16x16x32_f16 v[112:115], v[184:187], v[192:195], v[112:115]
	v_mfma_f32_16x16x32_f16 v[108:111], v[188:191], v[192:195], v[108:111]
	v_mfma_f32_16x16x32_f16 v[104:107], v[180:183], v[192:195], v[104:107]
	v_mfma_f32_16x16x32_f16 v[100:103], v[172:175], v[192:195], v[100:103]
	v_mfma_f32_16x16x32_f16 v[88:91], v[184:187], v[176:179], v[88:91]
	v_mfma_f32_16x16x32_f16 v[84:87], v[188:191], v[176:179], v[84:87]
	v_mfma_f32_16x16x32_f16 v[68:71], v[180:183], v[176:179], v[68:71]
	v_mfma_f32_16x16x32_f16 v[76:79], v[172:175], v[176:179], v[76:79]
	s_branch .Ls2_tail

.Lg4_loop:
	s_add_i32 s39, s38, 1
	s_cmp_ge_i32 s39, s3
	s_cbranch_scc1 .Lg4_cold
	s_add_i32 s38, s38, 2
	s_cmp_ge_i32 s38, s3
	s_cbranch_scc1 .Lg4_warm
	v_add_u32_e32 v246, v227, v228
	v_add_u32_e32 v247, v227, v231
	v_lshlrev_b32_e32 v246, 1, v246
	v_lshlrev_b32_e32 v247, 1, v247
	v_add_u32_e32 v248, 0x20000, v246
	v_add_u32_e32 v249, 0x40000, v246
	v_add_u32_e32 v250, 0x60000, v246
	v_add_u32_e32 v251, 0x20000, v247
	v_add_u32_e32 v252, 0x40000, v247
	v_add_u32_e32 v253, 0x60000, v247
	s_waitcnt lgkmcnt(7)
	v_mfma_f32_16x16x32_f16 v[156:159], v[176:179], v[164:167], v[156:159]
	v_mfma_f32_16x16x32_f16 v[128:131], v[176:179], v[168:171], v[128:131]
	v_mfma_f32_16x16x32_f16 v[96:99], v[176:179], v[172:175], v[96:99]
	v_mfma_f32_16x16x32_f16 v[80:83], v[176:179], v[192:195], v[80:83]
	s_waitcnt vmcnt(7)
	ds_write_b128 v254, v[100:103]
	global_load_dwordx4 v[100:103], v246, s[28:29] offset:256
	s_waitcnt lgkmcnt(7)
	v_mfma_f32_16x16x32_f16 v[152:155], v[180:183], v[164:167], v[152:155]
	v_mfma_f32_16x16x32_f16 v[120:123], v[180:183], v[168:171], v[120:123]
	v_mfma_f32_16x16x32_f16 v[92:95], v[180:183], v[172:175], v[92:95]
	v_mfma_f32_16x16x32_f16 v[76:79], v[180:183], v[192:195], v[76:79]
	s_waitcnt vmcnt(7)
	ds_write_b128 v254, v[108:111] offset:1024
	global_load_dwordx4 v[108:111], v248, s[28:29] offset:256
	s_waitcnt lgkmcnt(7)
	v_mfma_f32_16x16x32_f16 v[140:143], v[184:187], v[164:167], v[140:143]
	v_mfma_f32_16x16x32_f16 v[112:115], v[184:187], v[168:171], v[112:115]
	v_mfma_f32_16x16x32_f16 v[88:91], v[184:187], v[172:175], v[88:91]
	v_mfma_f32_16x16x32_f16 v[72:75], v[184:187], v[192:195], v[72:75]
	s_waitcnt vmcnt(7)
	ds_write_b128 v254, v[116:119] offset:2048
	global_load_dwordx4 v[116:119], v249, s[28:29] offset:256
	s_waitcnt lgkmcnt(7)
	v_mfma_f32_16x16x32_f16 v[136:139], v[188:191], v[164:167], v[136:139]
	v_mfma_f32_16x16x32_f16 v[104:107], v[188:191], v[168:171], v[104:107]
	v_mfma_f32_16x16x32_f16 v[84:87], v[188:191], v[172:175], v[84:87]
	v_mfma_f32_16x16x32_f16 v[68:71], v[188:191], v[192:195], v[68:71]
	s_waitcnt vmcnt(7)
	ds_write_b128 v254, v[124:127] offset:3072
	global_load_dwordx4 v[124:127], v250, s[28:29] offset:256
	ds_read_b128 v[164:167], v239
	ds_read_b128 v[168:171], v239 offset:256
	ds_read_b128 v[172:175], v239 offset:512
	ds_read_b128 v[192:195], v239 offset:768
	s_waitcnt lgkmcnt(11)
	v_mfma_f32_16x16x32_f16 v[64:67], v[176:179], v[196:199], v[64:67]
	s_waitcnt lgkmcnt(10)
	v_mfma_f32_16x16x32_f16 v[48:51], v[176:179], v[200:203], v[48:51]
	s_waitcnt lgkmcnt(9)
	v_mfma_f32_16x16x32_f16 v[30:33], v[176:179], v[204:207], v[30:33]
	s_waitcnt lgkmcnt(8)
	v_mfma_f32_16x16x32_f16 v[14:17], v[176:179], v[208:211], v[14:17]
	ds_read_b128 v[176:179], v237
	s_waitcnt vmcnt(7)
	ds_write_b128 v255, v[132:135]
	global_load_dwordx4 v[132:135], v247, s[30:31] offset:256
	v_mfma_f32_16x16x32_f16 v[60:63], v[180:183], v[196:199], v[60:63]
	v_mfma_f32_16x16x32_f16 v[44:47], v[180:183], v[200:203], v[44:47]
	v_mfma_f32_16x16x32_f16 v[26:29], v[180:183], v[204:207], v[26:29]
	v_mfma_f32_16x16x32_f16 v[10:13], v[180:183], v[208:211], v[10:13]
	ds_read_b128 v[180:183], v237 offset:256
	s_waitcnt vmcnt(7)
	ds_write_b128 v255, v[144:147] offset:1024
	global_load_dwordx4 v[144:147], v251, s[30:31] offset:256
	v_mfma_f32_16x16x32_f16 v[56:59], v[184:187], v[196:199], v[56:59]
	v_mfma_f32_16x16x32_f16 v[40:43], v[184:187], v[200:203], v[40:43]
	v_mfma_f32_16x16x32_f16 v[22:25], v[184:187], v[204:207], v[22:25]
	v_mfma_f32_16x16x32_f16 v[6:9], v[184:187], v[208:211], v[6:9]
	ds_read_b128 v[184:187], v237 offset:512
	s_waitcnt vmcnt(7)
	ds_write_b128 v255, v[148:151] offset:2048
	global_load_dwordx4 v[148:151], v252, s[30:31] offset:256
	v_mfma_f32_16x16x32_f16 v[52:55], v[188:191], v[196:199], v[52:55]
	v_mfma_f32_16x16x32_f16 v[36:39], v[188:191], v[200:203], v[36:39]
	v_mfma_f32_16x16x32_f16 v[18:21], v[188:191], v[204:207], v[18:21]
	v_mfma_f32_16x16x32_f16 v[2:5], v[188:191], v[208:211], v[2:5]
	ds_read_b128 v[188:191], v237 offset:768
	s_waitcnt vmcnt(7)
	ds_write_b128 v255, v[160:163] offset:3072
	global_load_dwordx4 v[160:163], v253, s[30:31] offset:256
	ds_read_b128 v[196:199], v239 offset:1024
	ds_read_b128 v[200:203], v239 offset:1280
	ds_read_b128 v[204:207], v239 offset:1536
	ds_read_b128 v[208:211], v239 offset:1792
	s_waitcnt lgkmcnt(11)
	v_mfma_f32_16x16x32_f16 v[156:159], v[176:179], v[164:167], v[156:159]
	v_mfma_f32_16x16x32_f16 v[128:131], v[176:179], v[168:171], v[128:131]
	v_mfma_f32_16x16x32_f16 v[96:99], v[176:179], v[172:175], v[96:99]
	v_mfma_f32_16x16x32_f16 v[80:83], v[176:179], v[192:195], v[80:83]
	s_waitcnt lgkmcnt(9)
	v_mfma_f32_16x16x32_f16 v[152:155], v[180:183], v[164:167], v[152:155]
	v_mfma_f32_16x16x32_f16 v[120:123], v[180:183], v[168:171], v[120:123]
	v_mfma_f32_16x16x32_f16 v[92:95], v[180:183], v[172:175], v[92:95]
	v_mfma_f32_16x16x32_f16 v[76:79], v[180:183], v[192:195], v[76:79]
	s_waitcnt lgkmcnt(7)
	v_mfma_f32_16x16x32_f16 v[140:143], v[184:187], v[164:167], v[140:143]
	v_mfma_f32_16x16x32_f16 v[112:115], v[184:187], v[168:171], v[112:115]
	v_mfma_f32_16x16x32_f16 v[88:91], v[184:187], v[172:175], v[88:91]
	v_mfma_f32_16x16x32_f16 v[72:75], v[184:187], v[192:195], v[72:75]
	s_waitcnt lgkmcnt(5)
	v_mfma_f32_16x16x32_f16 v[136:139], v[188:191], v[164:167], v[136:139]
	v_mfma_f32_16x16x32_f16 v[104:107], v[188:191], v[168:171], v[104:107]
	v_mfma_f32_16x16x32_f16 v[84:87], v[188:191], v[172:175], v[84:87]
	v_mfma_f32_16x16x32_f16 v[68:71], v[188:191], v[192:195], v[68:71]
	s_waitcnt lgkmcnt(0)
	s_barrier
	ds_read_b128 v[164:167], v238
	ds_read_b128 v[168:171], v238 offset:256
	ds_read_b128 v[172:175], v238 offset:512
	ds_read_b128 v[192:195], v238 offset:768
	v_mfma_f32_16x16x32_f16 v[64:67], v[176:179], v[196:199], v[64:67]
	v_mfma_f32_16x16x32_f16 v[48:51], v[176:179], v[200:203], v[48:51]
	v_mfma_f32_16x16x32_f16 v[30:33], v[176:179], v[204:207], v[30:33]
	v_mfma_f32_16x16x32_f16 v[14:17], v[176:179], v[208:211], v[14:17]
	ds_read_b128 v[176:179], v236
	v_mfma_f32_16x16x32_f16 v[60:63], v[180:183], v[196:199], v[60:63]
	v_mfma_f32_16x16x32_f16 v[44:47], v[180:183], v[200:203], v[44:47]
	v_mfma_f32_16x16x32_f16 v[26:29], v[180:183], v[204:207], v[26:29]
	v_mfma_f32_16x16x32_f16 v[10:13], v[180:183], v[208:211], v[10:13]
	ds_read_b128 v[180:183], v236 offset:256
	v_mfma_f32_16x16x32_f16 v[56:59], v[184:187], v[196:199], v[56:59]
	v_mfma_f32_16x16x32_f16 v[40:43], v[184:187], v[200:203], v[40:43]
	v_mfma_f32_16x16x32_f16 v[22:25], v[184:187], v[204:207], v[22:25]
	v_mfma_f32_16x16x32_f16 v[6:9], v[184:187], v[208:211], v[6:9]
	ds_read_b128 v[184:187], v236 offset:512
	v_mfma_f32_16x16x32_f16 v[52:55], v[188:191], v[196:199], v[52:55]
	v_mfma_f32_16x16x32_f16 v[36:39], v[188:191], v[200:203], v[36:39]
	v_mfma_f32_16x16x32_f16 v[18:21], v[188:191], v[204:207], v[18:21]
	v_mfma_f32_16x16x32_f16 v[2:5], v[188:191], v[208:211], v[2:5]
	ds_read_b128 v[188:191], v236 offset:768
	ds_read_b128 v[196:199], v238 offset:1024
	ds_read_b128 v[200:203], v238 offset:1280
	ds_read_b128 v[204:207], v238 offset:1536
	ds_read_b128 v[208:211], v238 offset:1792
	v_xor_b32_e32 v239, 0x8000, v239
	v_xor_b32_e32 v237, 0x8000, v237
	v_xor_b32_e32 v254, 0x8000, v254
	v_xor_b32_e32 v255, 0x8000, v255
	v_xor_b32_e32 v236, 0x8000, v236
	v_xor_b32_e32 v238, 0x8000, v238
	s_addk_i32 s23, 0x800
	v_add_u32_e32 v231, 64, v231
	v_add_u32_e32 v228, 64, v228
	s_mov_b32 s38, s39
	s_branch .Lg4_loop
.Lg4_warm:
	s_waitcnt lgkmcnt(7)
	v_mfma_f32_16x16x32_f16 v[156:159], v[176:179], v[164:167], v[156:159]
	v_mfma_f32_16x16x32_f16 v[128:131], v[176:179], v[168:171], v[128:131]
	v_mfma_f32_16x16x32_f16 v[96:99], v[176:179], v[172:175], v[96:99]
	v_mfma_f32_16x16x32_f16 v[80:83], v[176:179], v[192:195], v[80:83]
	s_waitcnt vmcnt(7)
	ds_write_b128 v254, v[100:103]
	s_waitcnt lgkmcnt(7)
	v_mfma_f32_16x16x32_f16 v[152:155], v[180:183], v[164:167], v[152:155]
	v_mfma_f32_16x16x32_f16 v[120:123], v[180:183], v[168:171], v[120:123]
	v_mfma_f32_16x16x32_f16 v[92:95], v[180:183], v[172:175], v[92:95]
	v_mfma_f32_16x16x32_f16 v[76:79], v[180:183], v[192:195], v[76:79]
	s_waitcnt vmcnt(6)
	ds_write_b128 v254, v[108:111] offset:1024
	s_waitcnt lgkmcnt(7)
	v_mfma_f32_16x16x32_f16 v[140:143], v[184:187], v[164:167], v[140:143]
	v_mfma_f32_16x16x32_f16 v[112:115], v[184:187], v[168:171], v[112:115]
	v_mfma_f32_16x16x32_f16 v[88:91], v[184:187], v[172:175], v[88:91]
	v_mfma_f32_16x16x32_f16 v[72:75], v[184:187], v[192:195], v[72:75]
	s_waitcnt vmcnt(5)
	ds_write_b128 v254, v[116:119] offset:2048
	s_waitcnt lgkmcnt(7)
	v_mfma_f32_16x16x32_f16 v[136:139], v[188:191], v[164:167], v[136:139]
	v_mfma_f32_16x16x32_f16 v[104:107], v[188:191], v[168:171], v[104:107]
	v_mfma_f32_16x16x32_f16 v[84:87], v[188:191], v[172:175], v[84:87]
	v_mfma_f32_16x16x32_f16 v[68:71], v[188:191], v[192:195], v[68:71]
	s_waitcnt vmcnt(4)
	ds_write_b128 v254, v[124:127] offset:3072
	ds_read_b128 v[164:167], v239
	ds_read_b128 v[168:171], v239 offset:256
	ds_read_b128 v[172:175], v239 offset:512
	ds_read_b128 v[192:195], v239 offset:768
	s_waitcnt lgkmcnt(11)
	v_mfma_f32_16x16x32_f16 v[64:67], v[176:179], v[196:199], v[64:67]
	s_waitcnt lgkmcnt(10)
	v_mfma_f32_16x16x32_f16 v[48:51], v[176:179], v[200:203], v[48:51]
	s_waitcnt lgkmcnt(9)
	v_mfma_f32_16x16x32_f16 v[30:33], v[176:179], v[204:207], v[30:33]
	s_waitcnt lgkmcnt(8)
	v_mfma_f32_16x16x32_f16 v[14:17], v[176:179], v[208:211], v[14:17]
	ds_read_b128 v[176:179], v237
	s_waitcnt vmcnt(3)
	ds_write_b128 v255, v[132:135]
	v_mfma_f32_16x16x32_f16 v[60:63], v[180:183], v[196:199], v[60:63]
	v_mfma_f32_16x16x32_f16 v[44:47], v[180:183], v[200:203], v[44:47]
	v_mfma_f32_16x16x32_f16 v[26:29], v[180:183], v[204:207], v[26:29]
	v_mfma_f32_16x16x32_f16 v[10:13], v[180:183], v[208:211], v[10:13]
	ds_read_b128 v[180:183], v237 offset:256
	s_waitcnt vmcnt(2)
	ds_write_b128 v255, v[144:147] offset:1024
	v_mfma_f32_16x16x32_f16 v[56:59], v[184:187], v[196:199], v[56:59]
	v_mfma_f32_16x16x32_f16 v[40:43], v[184:187], v[200:203], v[40:43]
	v_mfma_f32_16x16x32_f16 v[22:25], v[184:187], v[204:207], v[22:25]
	v_mfma_f32_16x16x32_f16 v[6:9], v[184:187], v[208:211], v[6:9]
	ds_read_b128 v[184:187], v237 offset:512
	s_waitcnt vmcnt(1)
	ds_write_b128 v255, v[148:151] offset:2048
	v_mfma_f32_16x16x32_f16 v[52:55], v[188:191], v[196:199], v[52:55]
	v_mfma_f32_16x16x32_f16 v[36:39], v[188:191], v[200:203], v[36:39]
	v_mfma_f32_16x16x32_f16 v[18:21], v[188:191], v[204:207], v[18:21]
	v_mfma_f32_16x16x32_f16 v[2:5], v[188:191], v[208:211], v[2:5]
	ds_read_b128 v[188:191], v237 offset:768
	s_waitcnt vmcnt(0)
	ds_write_b128 v255, v[160:163] offset:3072
	ds_read_b128 v[196:199], v239 offset:1024
	ds_read_b128 v[200:203], v239 offset:1280
	ds_read_b128 v[204:207], v239 offset:1536
	ds_read_b128 v[208:211], v239 offset:1792
	s_waitcnt lgkmcnt(11)
	v_mfma_f32_16x16x32_f16 v[156:159], v[176:179], v[164:167], v[156:159]
	v_mfma_f32_16x16x32_f16 v[128:131], v[176:179], v[168:171], v[128:131]
	v_mfma_f32_16x16x32_f16 v[96:99], v[176:179], v[172:175], v[96:99]
	v_mfma_f32_16x16x32_f16 v[80:83], v[176:179], v[192:195], v[80:83]
	s_waitcnt lgkmcnt(9)
	v_mfma_f32_16x16x32_f16 v[152:155], v[180:183], v[164:167], v[152:155]
	v_mfma_f32_16x16x32_f16 v[120:123], v[180:183], v[168:171], v[120:123]
	v_mfma_f32_16x16x32_f16 v[92:95], v[180:183], v[172:175], v[92:95]
	v_mfma_f32_16x16x32_f16 v[76:79], v[180:183], v[192:195], v[76:79]
	s_waitcnt lgkmcnt(7)
	v_mfma_f32_16x16x32_f16 v[140:143], v[184:187], v[164:167], v[140:143]
	v_mfma_f32_16x16x32_f16 v[112:115], v[184:187], v[168:171], v[112:115]
	v_mfma_f32_16x16x32_f16 v[88:91], v[184:187], v[172:175], v[88:91]
	v_mfma_f32_16x16x32_f16 v[72:75], v[184:187], v[192:195], v[72:75]
	s_waitcnt lgkmcnt(5)
	v_mfma_f32_16x16x32_f16 v[136:139], v[188:191], v[164:167], v[136:139]
	v_mfma_f32_16x16x32_f16 v[104:107], v[188:191], v[168:171], v[104:107]
	v_mfma_f32_16x16x32_f16 v[84:87], v[188:191], v[172:175], v[84:87]
	v_mfma_f32_16x16x32_f16 v[68:71], v[188:191], v[192:195], v[68:71]
	s_waitcnt lgkmcnt(0)
	s_barrier
	ds_read_b128 v[164:167], v238
	ds_read_b128 v[168:171], v238 offset:256
	ds_read_b128 v[172:175], v238 offset:512
	ds_read_b128 v[192:195], v238 offset:768
	v_mfma_f32_16x16x32_f16 v[64:67], v[176:179], v[196:199], v[64:67]
	v_mfma_f32_16x16x32_f16 v[48:51], v[176:179], v[200:203], v[48:51]
	v_mfma_f32_16x16x32_f16 v[30:33], v[176:179], v[204:207], v[30:33]
	v_mfma_f32_16x16x32_f16 v[14:17], v[176:179], v[208:211], v[14:17]
	ds_read_b128 v[176:179], v236
	v_mfma_f32_16x16x32_f16 v[60:63], v[180:183], v[196:199], v[60:63]
	v_mfma_f32_16x16x32_f16 v[44:47], v[180:183], v[200:203], v[44:47]
	v_mfma_f32_16x16x32_f16 v[26:29], v[180:183], v[204:207], v[26:29]
	v_mfma_f32_16x16x32_f16 v[10:13], v[180:183], v[208:211], v[10:13]
	ds_read_b128 v[180:183], v236 offset:256
	v_mfma_f32_16x16x32_f16 v[56:59], v[184:187], v[196:199], v[56:59]
	v_mfma_f32_16x16x32_f16 v[40:43], v[184:187], v[200:203], v[40:43]
	v_mfma_f32_16x16x32_f16 v[22:25], v[184:187], v[204:207], v[22:25]
	v_mfma_f32_16x16x32_f16 v[6:9], v[184:187], v[208:211], v[6:9]
	ds_read_b128 v[184:187], v236 offset:512
	v_mfma_f32_16x16x32_f16 v[52:55], v[188:191], v[196:199], v[52:55]
	v_mfma_f32_16x16x32_f16 v[36:39], v[188:191], v[200:203], v[36:39]
	v_mfma_f32_16x16x32_f16 v[18:21], v[188:191], v[204:207], v[18:21]
	v_mfma_f32_16x16x32_f16 v[2:5], v[188:191], v[208:211], v[2:5]
	ds_read_b128 v[188:191], v236 offset:768
	ds_read_b128 v[196:199], v238 offset:1024
	ds_read_b128 v[200:203], v238 offset:1280
	ds_read_b128 v[204:207], v238 offset:1536
	ds_read_b128 v[208:211], v238 offset:1792
	v_xor_b32_e32 v239, 0x8000, v239
	v_xor_b32_e32 v237, 0x8000, v237
	v_xor_b32_e32 v254, 0x8000, v254
	v_xor_b32_e32 v255, 0x8000, v255
	v_xor_b32_e32 v236, 0x8000, v236
	v_xor_b32_e32 v238, 0x8000, v238
	s_addk_i32 s23, 0x800
	v_add_u32_e32 v231, 64, v231
	v_add_u32_e32 v228, 64, v228
	s_mov_b32 s38, s39
	s_branch .Lg4_loop
.Lg4_cold:
	s_waitcnt lgkmcnt(7)
	v_mfma_f32_16x16x32_f16 v[156:159], v[176:179], v[164:167], v[156:159]
	v_mfma_f32_16x16x32_f16 v[128:131], v[176:179], v[168:171], v[128:131]
	v_mfma_f32_16x16x32_f16 v[96:99], v[176:179], v[172:175], v[96:99]
	v_mfma_f32_16x16x32_f16 v[80:83], v[176:179], v[192:195], v[80:83]
	s_waitcnt lgkmcnt(6)
	v_mfma_f32_16x16x32_f16 v[152:155], v[180:183], v[164:167], v[152:155]
	v_mfma_f32_16x16x32_f16 v[120:123], v[180:183], v[168:171], v[120:123]
	v_mfma_f32_16x16x32_f16 v[92:95], v[180:183], v[172:175], v[92:95]
	v_mfma_f32_16x16x32_f16 v[76:79], v[180:183], v[192:195], v[76:79]
	s_waitcnt lgkmcnt(5)
	v_mfma_f32_16x16x32_f16 v[140:143], v[184:187], v[164:167], v[140:143]
	v_mfma_f32_16x16x32_f16 v[112:115], v[184:187], v[168:171], v[112:115]
	v_mfma_f32_16x16x32_f16 v[88:91], v[184:187], v[172:175], v[88:91]
	v_mfma_f32_16x16x32_f16 v[72:75], v[184:187], v[192:195], v[72:75]
	s_waitcnt lgkmcnt(4)
	v_mfma_f32_16x16x32_f16 v[136:139], v[188:191], v[164:167], v[136:139]
	v_mfma_f32_16x16x32_f16 v[104:107], v[188:191], v[168:171], v[104:107]
	v_mfma_f32_16x16x32_f16 v[84:87], v[188:191], v[172:175], v[84:87]
	v_mfma_f32_16x16x32_f16 v[68:71], v[188:191], v[192:195], v[68:71]
	ds_read_b128 v[164:167], v239
	ds_read_b128 v[168:171], v239 offset:256
	ds_read_b128 v[172:175], v239 offset:512
	ds_read_b128 v[192:195], v239 offset:768
	s_waitcnt lgkmcnt(7)
	v_mfma_f32_16x16x32_f16 v[64:67], v[176:179], v[196:199], v[64:67]
	s_waitcnt lgkmcnt(6)
	v_mfma_f32_16x16x32_f16 v[48:51], v[176:179], v[200:203], v[48:51]
	s_waitcnt lgkmcnt(5)
	v_mfma_f32_16x16x32_f16 v[30:33], v[176:179], v[204:207], v[30:33]
	s_waitcnt lgkmcnt(4)
	v_mfma_f32_16x16x32_f16 v[14:17], v[176:179], v[208:211], v[14:17]
	ds_read_b128 v[176:179], v237
	v_mfma_f32_16x16x32_f16 v[60:63], v[180:183], v[196:199], v[60:63]
	v_mfma_f32_16x16x32_f16 v[44:47], v[180:183], v[200:203], v[44:47]
	v_mfma_f32_16x16x32_f16 v[26:29], v[180:183], v[204:207], v[26:29]
	v_mfma_f32_16x16x32_f16 v[10:13], v[180:183], v[208:211], v[10:13]
	ds_read_b128 v[180:183], v237 offset:256
	v_mfma_f32_16x16x32_f16 v[56:59], v[184:187], v[196:199], v[56:59]
	v_mfma_f32_16x16x32_f16 v[40:43], v[184:187], v[200:203], v[40:43]
	v_mfma_f32_16x16x32_f16 v[22:25], v[184:187], v[204:207], v[22:25]
	v_mfma_f32_16x16x32_f16 v[6:9], v[184:187], v[208:211], v[6:9]
	ds_read_b128 v[184:187], v237 offset:512
	v_mfma_f32_16x16x32_f16 v[52:55], v[188:191], v[196:199], v[52:55]
	v_mfma_f32_16x16x32_f16 v[36:39], v[188:191], v[200:203], v[36:39]
	v_mfma_f32_16x16x32_f16 v[18:21], v[188:191], v[204:207], v[18:21]
	v_mfma_f32_16x16x32_f16 v[2:5], v[188:191], v[208:211], v[2:5]
	ds_read_b128 v[188:191], v237 offset:768
	ds_read_b128 v[196:199], v239 offset:1024
	ds_read_b128 v[200:203], v239 offset:1280
	ds_read_b128 v[204:207], v239 offset:1536
	ds_read_b128 v[208:211], v239 offset:1792
	s_waitcnt lgkmcnt(7)
	v_mfma_f32_16x16x32_f16 v[156:159], v[176:179], v[164:167], v[156:159]
	v_mfma_f32_16x16x32_f16 v[128:131], v[176:179], v[168:171], v[128:131]
	v_mfma_f32_16x16x32_f16 v[96:99], v[176:179], v[172:175], v[96:99]
	v_mfma_f32_16x16x32_f16 v[80:83], v[176:179], v[192:195], v[80:83]
	s_waitcnt lgkmcnt(6)
	v_mfma_f32_16x16x32_f16 v[152:155], v[180:183], v[164:167], v[152:155]
	v_mfma_f32_16x16x32_f16 v[120:123], v[180:183], v[168:171], v[120:123]
	v_mfma_f32_16x16x32_f16 v[92:95], v[180:183], v[172:175], v[92:95]
	v_mfma_f32_16x16x32_f16 v[76:79], v[180:183], v[192:195], v[76:79]
	s_waitcnt lgkmcnt(5)
	v_mfma_f32_16x16x32_f16 v[140:143], v[184:187], v[164:167], v[140:143]
	v_mfma_f32_16x16x32_f16 v[112:115], v[184:187], v[168:171], v[112:115]
	v_mfma_f32_16x16x32_f16 v[88:91], v[184:187], v[172:175], v[88:91]
	v_mfma_f32_16x16x32_f16 v[72:75], v[184:187], v[192:195], v[72:75]
	s_waitcnt lgkmcnt(4)
	v_mfma_f32_16x16x32_f16 v[136:139], v[188:191], v[164:167], v[136:139]
	v_mfma_f32_16x16x32_f16 v[104:107], v[188:191], v[168:171], v[104:107]
	v_mfma_f32_16x16x32_f16 v[84:87], v[188:191], v[172:175], v[84:87]
	v_mfma_f32_16x16x32_f16 v[68:71], v[188:191], v[192:195], v[68:71]
	s_waitcnt lgkmcnt(0)
	s_barrier
	v_mfma_f32_16x16x32_f16 v[64:67], v[176:179], v[196:199], v[64:67]
	v_mfma_f32_16x16x32_f16 v[48:51], v[176:179], v[200:203], v[48:51]
	v_mfma_f32_16x16x32_f16 v[30:33], v[176:179], v[204:207], v[30:33]
	v_mfma_f32_16x16x32_f16 v[14:17], v[176:179], v[208:211], v[14:17]
	v_mfma_f32_16x16x32_f16 v[60:63], v[180:183], v[196:199], v[60:63]
	v_mfma_f32_16x16x32_f16 v[44:47], v[180:183], v[200:203], v[44:47]
	v_mfma_f32_16x16x32_f16 v[26:29], v[180:183], v[204:207], v[26:29]
	v_mfma_f32_16x16x32_f16 v[10:13], v[180:183], v[208:211], v[10:13]
	v_mfma_f32_16x16x32_f16 v[56:59], v[184:187], v[196:199], v[56:59]
	v_mfma_f32_16x16x32_f16 v[40:43], v[184:187], v[200:203], v[40:43]
	v_mfma_f32_16x16x32_f16 v[22:25], v[184:187], v[204:207], v[22:25]
	v_mfma_f32_16x16x32_f16 v[6:9], v[184:187], v[208:211], v[6:9]
	v_mfma_f32_16x16x32_f16 v[52:55], v[188:191], v[196:199], v[52:55]
	v_mfma_f32_16x16x32_f16 v[36:39], v[188:191], v[200:203], v[36:39]
	v_mfma_f32_16x16x32_f16 v[18:21], v[188:191], v[204:207], v[18:21]
	v_mfma_f32_16x16x32_f16 v[2:5], v[188:191], v[208:211], v[2:5]
	s_branch .LBB0_812
